# projection GEMM epilogue: row pairs exchanged with v_permlane16_swap, 32 global_store_dwordx2 per tile become 16 global_store_dwordx4 (same bytes, same addresses)
# speedup vs baseline: 1.0106x; 1.0106x over previous
;   DI void operator()(const f32x4 (&acc)[2][2][4][2], const pg8::Unit& u, int wr, int wc, int fr, int fq) const {
;     ...
;       int c1, c2;
;       if (mode == 2) { const int hb = gcol0 & ~63, g = wc & 1; c1 = hb + 16 * g + 4 * fq; c2 = c1 + 32; }
;       else { c1 = gcol0 + 4 * fq; c2 = c1 + 16; }
; #pragma unroll
;       for (int ai = 0; ai < 2; ++ai)
; #pragma unroll
;         for (int m = 0; m < 4; ++m) {
;           const int row = u.pm * 256 + ai * 128 + wr * 64 + m * 16 + fr;
;           f32x4 x1 = acc[ai][bj][m][0], x2 = acc[ai][bj][m][1];
;           if (mode != 0) {
;             const float pos = (float)(row & (S - 1));
; #pragma unroll
;             for (int e = 0; e < 4; ++e) {
;               const float ang = __fmul_rn(pos, invv[e]);
;               float sn, cs; sincos_big(ang, sn, cs);
;               const float y1 = x1[e] * cs - x2[e] * sn, y2 = x2[e] * cs + x1[e] * sn;
;               x1[e] = y1; x2[e] = y2;
;             }
;           }
;           u16* dp = proj + (size_t)row * NPROJ;
;           *(uint2*)(dp + c1) = make_uint2(pack2(x1[0] * scale, x1[1] * scale), pack2(x1[2] * scale, x1[3] * scale));
;           *(uint2*)(dp + c2) = make_uint2(pack2(x2[0] * scale, x2[1] * scale), pack2(x2[2] * scale, x2[3] * scale));
;           if (gcol0 >= 512 && gcol0 < 768) {
;             const int hd = (gcol0 - 512) >> 6, d0 = (gcol0 & 63) + 4 * fq;
;             unsigned char* vp = vt8 + ((size_t)((row >> 14) * 4 + hd) * 64 + d0) * S + (row & (S - 1));
;             const int w1a = __builtin_amdgcn_cvt_pk_fp8_f32(x1[0], x1[1], 0, false), w1b = __builtin_amdgcn_cvt_pk_fp8_f32(x1[2], x1[3], 0, false);
;             const int w2a = __builtin_amdgcn_cvt_pk_fp8_f32(x2[0], x2[1], 0, false), w2b = __builtin_amdgcn_cvt_pk_fp8_f32(x2[2], x2[3], 0, false);
;             vp[0] = (unsigned char)(w1a & 0xff); vp[(size_t)S] = (unsigned char)((w1a >> 8) & 0xff); vp[(size_t)2 * S] = (unsigned char)(w1b & 0xff); vp[(size_t)3 * S] = (unsigned char)((w1b >> 8) & 0xff);
;             unsigned char* vq = vp + (size_t)16 * S;
;             vq[0] = (unsigned char)(w2a & 0xff); vq[(size_t)S] = (unsigned char)((w2a >> 8) & 0xff); vq[(size_t)2 * S] = (unsigned char)(w2b & 0xff); vq[(size_t)3 * S] = (unsigned char)((w2b >> 8) & 0xff);
;           }
.LBB0_129:
	s_and_b32 s7, s20, 0xffffff40
	s_or_b32 s7, s7, s58
	s_and_b64 s[36:37], s[36:37], exec
	s_cselect_b32 s7, s7, s20
	s_cselect_b32 s21, 32, 16
	v_or_b32_e32 v174, s7, v180
	s_addk_i32 s20, 0xfe00
	s_ashr_i32 s7, s19, 12
	s_lshr_b32 s20, s20, 6
	s_and_b32 s7, s7, -4
	v_mov_b64_e32 v[168:169], s[28:29]
	v_ashrrev_i32_e32 v175, 31, v174
	s_or_b32 s36, s7, s20
	v_mad_i64_i32 v[168:169], s[42:43], v187, s9, v[168:169]
	v_pk_mul_f32 v[176:177], v[170:171], v[152:153] op_sel_hi:[0,1]
	v_pk_mul_f32 v[188:189], v[170:171], v[154:155] op_sel_hi:[0,1]
	v_or_b32_e32 v172, s21, v174
	s_ashr_i32 s37, s36, 31
	v_cvt_pk_bf16_f32 v176, v176, v177
	v_cvt_pk_bf16_f32 v177, v188, v189
	v_lshl_add_u64 v[188:189], v[174:175], 1, v[168:169]
	v_ashrrev_i32_e32 v173, 31, v172
	s_lshl_b64 s[40:41], s[36:37], 20
	v_bfe_u32 v222, v227, 4, 1
	v_mul_u32_u24_e32 v222, 0x17ff8, v222
	v_mov_b32_e32 v223, 0
	v_mov_b32_e32 v200, v176
	v_mov_b32_e32 v201, v177
	v_lshl_add_u64 v[204:205], v[188:189], 0, v[222:223]
	v_pk_mul_f32 v[176:177], v[170:171], v[148:149] op_sel_hi:[0,1]
	v_pk_mul_f32 v[188:189], v[170:171], v[150:151] op_sel_hi:[0,1]
	s_cmp_eq_u32 s18, 2
	v_cvt_pk_bf16_f32 v176, v176, v177
	v_cvt_pk_bf16_f32 v177, v188, v189
	v_lshl_add_u64 v[188:189], v[172:173], 1, v[168:169]
	s_cselect_b64 s[36:37], -1, 0
	s_cmp_lg_u32 s18, 2
	v_mov_b32_e32 v208, v176
	v_mov_b32_e32 v209, v177
	v_lshl_add_u64 v[212:213], v[188:189], 0, v[222:223]
	v_lshl_add_u64 v[176:177], v[162:163], 0, s[40:41]
	s_cbranch_scc1 .LBB0_131
	v_mov_b32_e32 v171, v1
	v_cvt_pk_fp8_f32 v171, v152, v153
	v_lshl_add_u64 v[188:189], v[176:177], 0, v[0:1]
	v_mov_b32_e32 v152, v1
	v_mov_b32_e32 v153, v1
	v_cvt_pk_fp8_f32 v152, v154, v155
	v_cvt_pk_fp8_f32 v153, v148, v149
	v_mov_b32_e32 v154, v1
	v_add_co_u32_e32 v148, vcc, 0x4000, v188
	v_cvt_pk_fp8_f32 v154, v150, v151
	v_lshrrev_b32_e32 v150, 8, v171
	v_addc_co_u32_e32 v149, vcc, 0, v189, vcc
	global_store_byte v[148:149], v150, off
	v_add_co_u32_e32 v148, vcc, 0x8000, v188
	v_lshrrev_b32_e32 v150, 8, v152
	s_nop 0
	v_addc_co_u32_e32 v149, vcc, 0, v189, vcc
	global_store_byte v[148:149], v152, off
	v_add_co_u32_e32 v148, vcc, 0xc000, v188
	global_store_byte v[188:189], v171, off
	s_nop 0
	v_addc_co_u32_e32 v149, vcc, 0, v189, vcc
	global_store_byte v[148:149], v150, off
	v_add_co_u32_e32 v148, vcc, 0x40000, v188
	v_lshrrev_b32_e32 v150, 8, v153
	s_nop 0
	v_addc_co_u32_e32 v149, vcc, 0, v189, vcc
	global_store_byte v[148:149], v153, off
	v_add_co_u32_e32 v148, vcc, 0x44000, v188
	s_nop 1
	v_addc_co_u32_e32 v149, vcc, 0, v189, vcc
	global_store_byte v[148:149], v150, off
	v_add_co_u32_e32 v148, vcc, 0x48000, v188
	v_lshrrev_b32_e32 v150, 8, v154
	s_nop 0
	v_addc_co_u32_e32 v149, vcc, 0, v189, vcc
	global_store_byte v[148:149], v154, off
	v_add_co_u32_e32 v148, vcc, 0x4c000, v188
	s_nop 1
	v_addc_co_u32_e32 v149, vcc, 0, v189, vcc
	global_store_byte v[148:149], v150, off

; DI unsigned pack2(float a, float b) { f2_t v = {a, b}; return __builtin_bit_cast(unsigned, __builtin_convertvector(v, bf2_t)); }
;   DI void operator()(const f32x4 (&acc)[2][2][4][2], const pg8::Unit& u, int wr, int wc, int fr, int fq) const {
;     ...
;           const int row = u.pm * 256 + ai * 128 + wr * 64 + m * 16 + fr;
;           f32x4 x1 = acc[ai][bj][m][0], x2 = acc[ai][bj][m][1];
;           if (mode != 0) {
;             const float pos = (float)(row & (S - 1));
; #pragma unroll
;             for (int e = 0; e < 4; ++e) {
;               const float ang = __fmul_rn(pos, invv[e]);
;               float sn, cs; sincos_big(ang, sn, cs);
;               const float y1 = x1[e] * cs - x2[e] * sn, y2 = x2[e] * cs + x1[e] * sn;
;               x1[e] = y1; x2[e] = y2;
;             }
;           }
;           u16* dp = proj + (size_t)row * NPROJ;
;           *(uint2*)(dp + c1) = make_uint2(pack2(x1[0] * scale, x1[1] * scale), pack2(x1[2] * scale, x1[3] * scale));
;           *(uint2*)(dp + c2) = make_uint2(pack2(x2[0] * scale, x2[1] * scale), pack2(x2[2] * scale, x2[3] * scale));
;           if (gcol0 >= 512 && gcol0 < 768) {
;             const int hd = (gcol0 - 512) >> 6, d0 = (gcol0 & 63) + 4 * fq;
;             unsigned char* vp = vt8 + ((size_t)((row >> 14) * 4 + hd) * 64 + d0) * S + (row & (S - 1));
;             const int w1a = __builtin_amdgcn_cvt_pk_fp8_f32(x1[0], x1[1], 0, false), w1b = __builtin_amdgcn_cvt_pk_fp8_f32(x1[2], x1[3], 0, false);
;             const int w2a = __builtin_amdgcn_cvt_pk_fp8_f32(x2[0], x2[1], 0, false), w2b = __builtin_amdgcn_cvt_pk_fp8_f32(x2[2], x2[3], 0, false);
;             vp[0] = (unsigned char)(w1a & 0xff); vp[(size_t)S] = (unsigned char)((w1a >> 8) & 0xff); vp[(size_t)2 * S] = (unsigned char)(w1b & 0xff); vp[(size_t)3 * S] = (unsigned char)((w1b >> 8) & 0xff);
;             unsigned char* vq = vp + (size_t)16 * S;
;             vq[0] = (unsigned char)(w2a & 0xff); vq[(size_t)S] = (unsigned char)((w2a >> 8) & 0xff); vq[(size_t)2 * S] = (unsigned char)(w2b & 0xff); vq[(size_t)3 * S] = (unsigned char)((w2b >> 8) & 0xff);
;           }
.LBB0_133:
	v_mov_b32_e32 v171, v170
	v_mov_b64_e32 v[150:151], s[28:29]
	v_mad_i64_i32 v[150:151], s[16:17], v149, s9, v[150:151]
	v_pk_mul_f32 v[154:155], v[170:171], v[144:145]
	v_pk_mul_f32 v[188:189], v[170:171], v[146:147]
	v_cvt_pk_bf16_f32 v154, v154, v155
	v_cvt_pk_bf16_f32 v155, v188, v189
	v_lshl_add_u64 v[188:189], v[174:175], 1, v[150:151]
	v_mov_b32_e32 v202, v154
	v_mov_b32_e32 v203, v155
	s_nop 1
	v_permlane16_swap_b32_e32 v200, v202
	v_permlane16_swap_b32_e32 v201, v203
	global_store_dwordx4 v[204:205], v[200:203], off
	v_pk_mul_f32 v[154:155], v[170:171], v[140:141]
	v_pk_mul_f32 v[188:189], v[170:171], v[142:143]
	v_cndmask_b32_e64 v149, 0, 1, s[36:37]
	v_cvt_pk_bf16_f32 v154, v154, v155
	v_cvt_pk_bf16_f32 v155, v188, v189
	v_lshl_add_u64 v[188:189], v[172:173], 1, v[150:151]
	v_cmp_ne_u32_e64 s[40:41], 1, v149
	s_andn2_b64 vcc, exec, s[36:37]
	v_mov_b32_e32 v210, v154
	v_mov_b32_e32 v211, v155
	s_nop 1
	v_permlane16_swap_b32_e32 v208, v210
	v_permlane16_swap_b32_e32 v209, v211
	global_store_dwordx4 v[212:213], v[208:211], off
	s_cbranch_vccnz .LBB0_135
	v_mov_b32_e32 v149, v1
	v_lshl_add_u64 v[154:155], v[176:177], 0, v[148:149]
	v_cvt_pk_fp8_f32 v149, v144, v145
	v_mov_b32_e32 v144, v1
	v_mov_b32_e32 v145, v1
	v_cvt_pk_fp8_f32 v144, v146, v147
	v_cvt_pk_fp8_f32 v145, v140, v141
	v_mov_b32_e32 v146, v1
	v_add_co_u32_e32 v140, vcc, 0x4000, v154
	v_cvt_pk_fp8_f32 v146, v142, v143
	v_lshrrev_b32_e32 v142, 8, v149
	v_addc_co_u32_e32 v141, vcc, 0, v155, vcc
	global_store_byte v[140:141], v142, off
	v_add_co_u32_e32 v140, vcc, 0x8000, v154
	v_lshrrev_b32_e32 v142, 8, v144
	s_nop 0
	v_addc_co_u32_e32 v141, vcc, 0, v155, vcc
	global_store_byte v[140:141], v144, off
	v_add_co_u32_e32 v140, vcc, 0xc000, v154
	global_store_byte v[154:155], v149, off
	s_nop 0
	v_addc_co_u32_e32 v141, vcc, 0, v155, vcc
	global_store_byte v[140:141], v142, off
	v_add_co_u32_e32 v140, vcc, 0x40000, v154
	v_lshrrev_b32_e32 v142, 8, v145
	s_nop 0
	v_addc_co_u32_e32 v141, vcc, 0, v155, vcc
	global_store_byte v[140:141], v145, off
	v_add_co_u32_e32 v140, vcc, 0x44000, v154
	s_nop 1
	v_addc_co_u32_e32 v141, vcc, 0, v155, vcc
	global_store_byte v[140:141], v142, off
	v_add_co_u32_e32 v140, vcc, 0x48000, v154
	v_lshrrev_b32_e32 v142, 8, v146
	s_nop 0
	v_addc_co_u32_e32 v141, vcc, 0, v155, vcc
	global_store_byte v[140:141], v146, off
	v_add_co_u32_e32 v140, vcc, 0x4c000, v154
	s_nop 1
	v_addc_co_u32_e32 v141, vcc, 0, v155, vcc
	global_store_byte v[140:141], v142, off

; DI unsigned pack2(float a, float b) { f2_t v = {a, b}; return __builtin_bit_cast(unsigned, __builtin_convertvector(v, bf2_t)); }
;   DI void operator()(const f32x4 (&acc)[2][2][4][2], const pg8::Unit& u, int wr, int wc, int fr, int fq) const {
;     ...
;           const int row = u.pm * 256 + ai * 128 + wr * 64 + m * 16 + fr;
;           f32x4 x1 = acc[ai][bj][m][0], x2 = acc[ai][bj][m][1];
;           if (mode != 0) {
;             const float pos = (float)(row & (S - 1));
; #pragma unroll
;             for (int e = 0; e < 4; ++e) {
;               const float ang = __fmul_rn(pos, invv[e]);
;               float sn, cs; sincos_big(ang, sn, cs);
;               const float y1 = x1[e] * cs - x2[e] * sn, y2 = x2[e] * cs + x1[e] * sn;
;               x1[e] = y1; x2[e] = y2;
;             }
;           }
;           u16* dp = proj + (size_t)row * NPROJ;
;           *(uint2*)(dp + c1) = make_uint2(pack2(x1[0] * scale, x1[1] * scale), pack2(x1[2] * scale, x1[3] * scale));
;           *(uint2*)(dp + c2) = make_uint2(pack2(x2[0] * scale, x2[1] * scale), pack2(x2[2] * scale, x2[3] * scale));
;           if (gcol0 >= 512 && gcol0 < 768) {
;             const int hd = (gcol0 - 512) >> 6, d0 = (gcol0 & 63) + 4 * fq;
;             unsigned char* vp = vt8 + ((size_t)((row >> 14) * 4 + hd) * 64 + d0) * S + (row & (S - 1));
;             const int w1a = __builtin_amdgcn_cvt_pk_fp8_f32(x1[0], x1[1], 0, false), w1b = __builtin_amdgcn_cvt_pk_fp8_f32(x1[2], x1[3], 0, false);
;             const int w2a = __builtin_amdgcn_cvt_pk_fp8_f32(x2[0], x2[1], 0, false), w2b = __builtin_amdgcn_cvt_pk_fp8_f32(x2[2], x2[3], 0, false);
;             vp[0] = (unsigned char)(w1a & 0xff); vp[(size_t)S] = (unsigned char)((w1a >> 8) & 0xff); vp[(size_t)2 * S] = (unsigned char)(w1b & 0xff); vp[(size_t)3 * S] = (unsigned char)((w1b >> 8) & 0xff);
;             unsigned char* vq = vp + (size_t)16 * S;
;             vq[0] = (unsigned char)(w2a & 0xff); vq[(size_t)S] = (unsigned char)((w2a >> 8) & 0xff); vq[(size_t)2 * S] = (unsigned char)(w2b & 0xff); vq[(size_t)3 * S] = (unsigned char)((w2b >> 8) & 0xff);
;           }
.LBB0_137:
	v_mov_b64_e32 v[142:143], s[28:29]
	v_mad_i64_i32 v[142:143], s[16:17], v141, s9, v[142:143]
	v_pk_mul_f32 v[146:147], v[170:171], v[136:137]
	v_pk_mul_f32 v[154:155], v[170:171], v[138:139]
	v_cvt_pk_bf16_f32 v146, v146, v147
	v_cvt_pk_bf16_f32 v147, v154, v155
	v_lshl_add_u64 v[154:155], v[174:175], 1, v[142:143]
	v_bfe_u32 v222, v227, 4, 1
	v_mul_u32_u24_e32 v222, 0x17ff8, v222
	v_mov_b32_e32 v223, 0
	v_mov_b32_e32 v200, v146
	v_mov_b32_e32 v201, v147
	v_lshl_add_u64 v[204:205], v[154:155], 0, v[222:223]
	v_pk_mul_f32 v[146:147], v[170:171], v[132:133]
	v_pk_mul_f32 v[154:155], v[170:171], v[134:135]
	v_cvt_pk_bf16_f32 v146, v146, v147
	v_cvt_pk_bf16_f32 v147, v154, v155
	v_lshl_add_u64 v[154:155], v[172:173], 1, v[142:143]
	s_and_b64 vcc, exec, s[40:41]
	v_mov_b32_e32 v208, v146
	v_mov_b32_e32 v209, v147
	v_lshl_add_u64 v[212:213], v[154:155], 0, v[222:223]
	s_cbranch_vccnz .LBB0_139
	v_mov_b32_e32 v141, v1
	v_lshl_add_u64 v[146:147], v[176:177], 0, v[140:141]
	v_cvt_pk_fp8_f32 v141, v136, v137
	v_mov_b32_e32 v136, v1
	v_mov_b32_e32 v137, v1
	v_cvt_pk_fp8_f32 v136, v138, v139
	v_cvt_pk_fp8_f32 v137, v132, v133
	v_mov_b32_e32 v138, v1
	v_add_co_u32_e32 v132, vcc, 0x4000, v146
	v_cvt_pk_fp8_f32 v138, v134, v135
	v_lshrrev_b32_e32 v134, 8, v141
	v_addc_co_u32_e32 v133, vcc, 0, v147, vcc
	global_store_byte v[132:133], v134, off
	v_add_co_u32_e32 v132, vcc, 0x8000, v146
	v_lshrrev_b32_e32 v134, 8, v136
	s_nop 0
	v_addc_co_u32_e32 v133, vcc, 0, v147, vcc
	global_store_byte v[132:133], v136, off
	v_add_co_u32_e32 v132, vcc, 0xc000, v146
	global_store_byte v[146:147], v141, off
	s_nop 0
	v_addc_co_u32_e32 v133, vcc, 0, v147, vcc
	global_store_byte v[132:133], v134, off
	v_add_co_u32_e32 v132, vcc, 0x40000, v146
	v_lshrrev_b32_e32 v134, 8, v137
	s_nop 0
	v_addc_co_u32_e32 v133, vcc, 0, v147, vcc
	global_store_byte v[132:133], v137, off
	v_add_co_u32_e32 v132, vcc, 0x44000, v146
	s_nop 1
	v_addc_co_u32_e32 v133, vcc, 0, v147, vcc
	global_store_byte v[132:133], v134, off
	v_add_co_u32_e32 v132, vcc, 0x48000, v146
	v_lshrrev_b32_e32 v134, 8, v138
	s_nop 0
	v_addc_co_u32_e32 v133, vcc, 0, v147, vcc
	global_store_byte v[132:133], v138, off
	v_add_co_u32_e32 v132, vcc, 0x4c000, v146
	s_nop 1
	v_addc_co_u32_e32 v133, vcc, 0, v147, vcc
	global_store_byte v[132:133], v134, off

; DI unsigned pack2(float a, float b) { f2_t v = {a, b}; return __builtin_bit_cast(unsigned, __builtin_convertvector(v, bf2_t)); }
;   DI void operator()(const f32x4 (&acc)[2][2][4][2], const pg8::Unit& u, int wr, int wc, int fr, int fq) const {
;     ...
;           const int row = u.pm * 256 + ai * 128 + wr * 64 + m * 16 + fr;
;           f32x4 x1 = acc[ai][bj][m][0], x2 = acc[ai][bj][m][1];
;           if (mode != 0) {
;             const float pos = (float)(row & (S - 1));
; #pragma unroll
;             for (int e = 0; e < 4; ++e) {
;               const float ang = __fmul_rn(pos, invv[e]);
;               float sn, cs; sincos_big(ang, sn, cs);
;               const float y1 = x1[e] * cs - x2[e] * sn, y2 = x2[e] * cs + x1[e] * sn;
;               x1[e] = y1; x2[e] = y2;
;             }
;           }
;           u16* dp = proj + (size_t)row * NPROJ;
;           *(uint2*)(dp + c1) = make_uint2(pack2(x1[0] * scale, x1[1] * scale), pack2(x1[2] * scale, x1[3] * scale));
;           *(uint2*)(dp + c2) = make_uint2(pack2(x2[0] * scale, x2[1] * scale), pack2(x2[2] * scale, x2[3] * scale));
;           if (gcol0 >= 512 && gcol0 < 768) {
;             const int hd = (gcol0 - 512) >> 6, d0 = (gcol0 & 63) + 4 * fq;
;             unsigned char* vp = vt8 + ((size_t)((row >> 14) * 4 + hd) * 64 + d0) * S + (row & (S - 1));
;             const int w1a = __builtin_amdgcn_cvt_pk_fp8_f32(x1[0], x1[1], 0, false), w1b = __builtin_amdgcn_cvt_pk_fp8_f32(x1[2], x1[3], 0, false);
;             const int w2a = __builtin_amdgcn_cvt_pk_fp8_f32(x2[0], x2[1], 0, false), w2b = __builtin_amdgcn_cvt_pk_fp8_f32(x2[2], x2[3], 0, false);
;             vp[0] = (unsigned char)(w1a & 0xff); vp[(size_t)S] = (unsigned char)((w1a >> 8) & 0xff); vp[(size_t)2 * S] = (unsigned char)(w1b & 0xff); vp[(size_t)3 * S] = (unsigned char)((w1b >> 8) & 0xff);
;             unsigned char* vq = vp + (size_t)16 * S;
;             vq[0] = (unsigned char)(w2a & 0xff); vq[(size_t)S] = (unsigned char)((w2a >> 8) & 0xff); vq[(size_t)2 * S] = (unsigned char)(w2b & 0xff); vq[(size_t)3 * S] = (unsigned char)((w2b >> 8) & 0xff);
;           }
.LBB0_141:
	v_mov_b64_e32 v[134:135], s[28:29]
	v_mad_i64_i32 v[134:135], s[16:17], v133, s9, v[134:135]
	v_pk_mul_f32 v[138:139], v[170:171], v[128:129]
	v_pk_mul_f32 v[146:147], v[170:171], v[130:131]
	v_cvt_pk_bf16_f32 v138, v138, v139
	v_cvt_pk_bf16_f32 v139, v146, v147
	v_lshl_add_u64 v[146:147], v[174:175], 1, v[134:135]
	v_mov_b32_e32 v202, v138
	v_mov_b32_e32 v203, v139
	s_nop 1
	v_permlane16_swap_b32_e32 v200, v202
	v_permlane16_swap_b32_e32 v201, v203
	global_store_dwordx4 v[204:205], v[200:203], off
	v_pk_mul_f32 v[138:139], v[170:171], v[124:125]
	v_pk_mul_f32 v[146:147], v[170:171], v[126:127]
	v_cvt_pk_bf16_f32 v138, v138, v139
	v_cvt_pk_bf16_f32 v139, v146, v147
	v_lshl_add_u64 v[146:147], v[172:173], 1, v[134:135]
	s_and_b64 vcc, exec, s[40:41]
	v_mov_b32_e32 v210, v138
	v_mov_b32_e32 v211, v139
	s_nop 1
	v_permlane16_swap_b32_e32 v208, v210
	v_permlane16_swap_b32_e32 v209, v211
	global_store_dwordx4 v[212:213], v[208:211], off
	s_cbranch_vccnz .LBB0_143
	v_mov_b32_e32 v133, v1
	v_lshl_add_u64 v[138:139], v[176:177], 0, v[132:133]
	v_cvt_pk_fp8_f32 v133, v128, v129
	v_mov_b32_e32 v128, v1
	v_mov_b32_e32 v129, v1
	v_cvt_pk_fp8_f32 v128, v130, v131
	v_cvt_pk_fp8_f32 v129, v124, v125
	v_mov_b32_e32 v130, v1
	v_add_co_u32_e32 v124, vcc, 0x4000, v138
	v_cvt_pk_fp8_f32 v130, v126, v127
	v_lshrrev_b32_e32 v126, 8, v133
	v_addc_co_u32_e32 v125, vcc, 0, v139, vcc
	global_store_byte v[124:125], v126, off
	v_add_co_u32_e32 v124, vcc, 0x8000, v138
	v_lshrrev_b32_e32 v126, 8, v128
	s_nop 0
	v_addc_co_u32_e32 v125, vcc, 0, v139, vcc
	global_store_byte v[124:125], v128, off
	v_add_co_u32_e32 v124, vcc, 0xc000, v138
	global_store_byte v[138:139], v133, off
	s_nop 0
	v_addc_co_u32_e32 v125, vcc, 0, v139, vcc
	global_store_byte v[124:125], v126, off
	v_add_co_u32_e32 v124, vcc, 0x40000, v138
	v_lshrrev_b32_e32 v126, 8, v129
	s_nop 0
	v_addc_co_u32_e32 v125, vcc, 0, v139, vcc
	global_store_byte v[124:125], v129, off
	v_add_co_u32_e32 v124, vcc, 0x44000, v138
	s_nop 1
	v_addc_co_u32_e32 v125, vcc, 0, v139, vcc
	global_store_byte v[124:125], v126, off
	v_add_co_u32_e32 v124, vcc, 0x48000, v138
	v_lshrrev_b32_e32 v126, 8, v130
	s_nop 0
	v_addc_co_u32_e32 v125, vcc, 0, v139, vcc
	global_store_byte v[124:125], v130, off
	v_add_co_u32_e32 v124, vcc, 0x4c000, v138
	s_nop 1
	v_addc_co_u32_e32 v125, vcc, 0, v139, vcc
	global_store_byte v[124:125], v126, off

; DI unsigned pack2(float a, float b) { f2_t v = {a, b}; return __builtin_bit_cast(unsigned, __builtin_convertvector(v, bf2_t)); }
;   DI void operator()(const f32x4 (&acc)[2][2][4][2], const pg8::Unit& u, int wr, int wc, int fr, int fq) const {
;     ...
;           const int row = u.pm * 256 + ai * 128 + wr * 64 + m * 16 + fr;
;           f32x4 x1 = acc[ai][bj][m][0], x2 = acc[ai][bj][m][1];
;           if (mode != 0) {
;             const float pos = (float)(row & (S - 1));
; #pragma unroll
;             for (int e = 0; e < 4; ++e) {
;               const float ang = __fmul_rn(pos, invv[e]);
;               float sn, cs; sincos_big(ang, sn, cs);
;               const float y1 = x1[e] * cs - x2[e] * sn, y2 = x2[e] * cs + x1[e] * sn;
;               x1[e] = y1; x2[e] = y2;
;             }
;           }
;           u16* dp = proj + (size_t)row * NPROJ;
;           *(uint2*)(dp + c1) = make_uint2(pack2(x1[0] * scale, x1[1] * scale), pack2(x1[2] * scale, x1[3] * scale));
;           *(uint2*)(dp + c2) = make_uint2(pack2(x2[0] * scale, x2[1] * scale), pack2(x2[2] * scale, x2[3] * scale));
;           if (gcol0 >= 512 && gcol0 < 768) {
;             const int hd = (gcol0 - 512) >> 6, d0 = (gcol0 & 63) + 4 * fq;
;             unsigned char* vp = vt8 + ((size_t)((row >> 14) * 4 + hd) * 64 + d0) * S + (row & (S - 1));
;             const int w1a = __builtin_amdgcn_cvt_pk_fp8_f32(x1[0], x1[1], 0, false), w1b = __builtin_amdgcn_cvt_pk_fp8_f32(x1[2], x1[3], 0, false);
;             const int w2a = __builtin_amdgcn_cvt_pk_fp8_f32(x2[0], x2[1], 0, false), w2b = __builtin_amdgcn_cvt_pk_fp8_f32(x2[2], x2[3], 0, false);
;             vp[0] = (unsigned char)(w1a & 0xff); vp[(size_t)S] = (unsigned char)((w1a >> 8) & 0xff); vp[(size_t)2 * S] = (unsigned char)(w1b & 0xff); vp[(size_t)3 * S] = (unsigned char)((w1b >> 8) & 0xff);
;             unsigned char* vq = vp + (size_t)16 * S;
;             vq[0] = (unsigned char)(w2a & 0xff); vq[(size_t)S] = (unsigned char)((w2a >> 8) & 0xff); vq[(size_t)2 * S] = (unsigned char)(w2b & 0xff); vq[(size_t)3 * S] = (unsigned char)((w2b >> 8) & 0xff);
;           }
.LBB0_145:
	s_ashr_i32 s16, s19, 12
	s_and_b32 s18, s16, -4
	v_mov_b64_e32 v[126:127], s[28:29]
	s_or_b32 s16, s18, s20
	v_mad_i64_i32 v[126:127], s[20:21], v131, s9, v[126:127]
	v_pk_mul_f32 v[128:129], v[170:171], v[120:121]
	v_pk_mul_f32 v[138:139], v[170:171], v[122:123]
	v_cvt_pk_bf16_f32 v128, v128, v129
	v_cvt_pk_bf16_f32 v129, v138, v139
	v_lshl_add_u64 v[138:139], v[174:175], 1, v[126:127]
	s_ashr_i32 s17, s16, 31
	v_bfe_u32 v222, v227, 4, 1
	v_mul_u32_u24_e32 v222, 0x17ff8, v222
	v_mov_b32_e32 v223, 0
	v_mov_b32_e32 v200, v128
	v_mov_b32_e32 v201, v129
	v_lshl_add_u64 v[204:205], v[138:139], 0, v[222:223]
	v_pk_mul_f32 v[128:129], v[170:171], v[116:117]
	v_pk_mul_f32 v[138:139], v[170:171], v[118:119]
	s_lshl_b64 s[16:17], s[16:17], 20
	v_cvt_pk_bf16_f32 v128, v128, v129
	v_cvt_pk_bf16_f32 v129, v138, v139
	v_lshl_add_u64 v[138:139], v[172:173], 1, v[126:127]
	v_mov_b32_e32 v208, v128
	v_mov_b32_e32 v209, v129
	v_lshl_add_u64 v[212:213], v[138:139], 0, v[222:223]
	s_and_b64 vcc, exec, s[40:41]
	v_lshl_add_u64 v[128:129], v[162:163], 0, s[16:17]
	s_cbranch_vccnz .LBB0_147
	v_mov_b32_e32 v125, v1
	v_lshl_add_u64 v[138:139], v[128:129], 0, v[124:125]
	v_cvt_pk_fp8_f32 v125, v120, v121
	v_mov_b32_e32 v120, v1
	v_mov_b32_e32 v121, v1
	v_cvt_pk_fp8_f32 v120, v122, v123
	v_cvt_pk_fp8_f32 v121, v116, v117
	v_mov_b32_e32 v122, v1
	v_add_co_u32_e32 v116, vcc, 0x4000, v138
	v_cvt_pk_fp8_f32 v122, v118, v119
	v_lshrrev_b32_e32 v118, 8, v125
	v_addc_co_u32_e32 v117, vcc, 0, v139, vcc
	global_store_byte v[116:117], v118, off
	v_add_co_u32_e32 v116, vcc, 0x8000, v138
	v_lshrrev_b32_e32 v118, 8, v120
	s_nop 0
	v_addc_co_u32_e32 v117, vcc, 0, v139, vcc
	global_store_byte v[116:117], v120, off
	v_add_co_u32_e32 v116, vcc, 0xc000, v138
	global_store_byte v[138:139], v125, off
	s_nop 0
	v_addc_co_u32_e32 v117, vcc, 0, v139, vcc
	global_store_byte v[116:117], v118, off
	v_add_co_u32_e32 v116, vcc, 0x40000, v138
	v_lshrrev_b32_e32 v118, 8, v121
	s_nop 0
	v_addc_co_u32_e32 v117, vcc, 0, v139, vcc
	global_store_byte v[116:117], v121, off
	v_add_co_u32_e32 v116, vcc, 0x44000, v138
	s_nop 1
	v_addc_co_u32_e32 v117, vcc, 0, v139, vcc
	global_store_byte v[116:117], v118, off
	v_add_co_u32_e32 v116, vcc, 0x48000, v138
	v_lshrrev_b32_e32 v118, 8, v122
	s_nop 0
	v_addc_co_u32_e32 v117, vcc, 0, v139, vcc
	global_store_byte v[116:117], v122, off
	v_add_co_u32_e32 v116, vcc, 0x4c000, v138
	s_nop 1
	v_addc_co_u32_e32 v117, vcc, 0, v139, vcc
	global_store_byte v[116:117], v118, off

; DI unsigned pack2(float a, float b) { f2_t v = {a, b}; return __builtin_bit_cast(unsigned, __builtin_convertvector(v, bf2_t)); }
;   DI void operator()(const f32x4 (&acc)[2][2][4][2], const pg8::Unit& u, int wr, int wc, int fr, int fq) const {
;     ...
;           const int row = u.pm * 256 + ai * 128 + wr * 64 + m * 16 + fr;
;           f32x4 x1 = acc[ai][bj][m][0], x2 = acc[ai][bj][m][1];
;           if (mode != 0) {
;             const float pos = (float)(row & (S - 1));
; #pragma unroll
;             for (int e = 0; e < 4; ++e) {
;               const float ang = __fmul_rn(pos, invv[e]);
;               float sn, cs; sincos_big(ang, sn, cs);
;               const float y1 = x1[e] * cs - x2[e] * sn, y2 = x2[e] * cs + x1[e] * sn;
;               x1[e] = y1; x2[e] = y2;
;             }
;           }
;           u16* dp = proj + (size_t)row * NPROJ;
;           *(uint2*)(dp + c1) = make_uint2(pack2(x1[0] * scale, x1[1] * scale), pack2(x1[2] * scale, x1[3] * scale));
;           *(uint2*)(dp + c2) = make_uint2(pack2(x2[0] * scale, x2[1] * scale), pack2(x2[2] * scale, x2[3] * scale));
;           if (gcol0 >= 512 && gcol0 < 768) {
;             const int hd = (gcol0 - 512) >> 6, d0 = (gcol0 & 63) + 4 * fq;
;             unsigned char* vp = vt8 + ((size_t)((row >> 14) * 4 + hd) * 64 + d0) * S + (row & (S - 1));
;             const int w1a = __builtin_amdgcn_cvt_pk_fp8_f32(x1[0], x1[1], 0, false), w1b = __builtin_amdgcn_cvt_pk_fp8_f32(x1[2], x1[3], 0, false);
;             const int w2a = __builtin_amdgcn_cvt_pk_fp8_f32(x2[0], x2[1], 0, false), w2b = __builtin_amdgcn_cvt_pk_fp8_f32(x2[2], x2[3], 0, false);
;             vp[0] = (unsigned char)(w1a & 0xff); vp[(size_t)S] = (unsigned char)((w1a >> 8) & 0xff); vp[(size_t)2 * S] = (unsigned char)(w1b & 0xff); vp[(size_t)3 * S] = (unsigned char)((w1b >> 8) & 0xff);
;             unsigned char* vq = vp + (size_t)16 * S;
;             vq[0] = (unsigned char)(w2a & 0xff); vq[(size_t)S] = (unsigned char)((w2a >> 8) & 0xff); vq[(size_t)2 * S] = (unsigned char)(w2b & 0xff); vq[(size_t)3 * S] = (unsigned char)((w2b >> 8) & 0xff);
;           }
.LBB0_149:
	v_mov_b64_e32 v[118:119], s[28:29]
	v_mad_i64_i32 v[118:119], s[16:17], v117, s9, v[118:119]
	v_pk_mul_f32 v[122:123], v[170:171], v[104:105]
	v_pk_mul_f32 v[138:139], v[170:171], v[106:107]
	v_cvt_pk_bf16_f32 v122, v122, v123
	v_cvt_pk_bf16_f32 v123, v138, v139
	v_lshl_add_u64 v[138:139], v[174:175], 1, v[118:119]
	v_mov_b32_e32 v202, v122
	v_mov_b32_e32 v203, v123
	s_nop 1
	v_permlane16_swap_b32_e32 v200, v202
	v_permlane16_swap_b32_e32 v201, v203
	global_store_dwordx4 v[204:205], v[200:203], off
	v_pk_mul_f32 v[122:123], v[170:171], v[100:101]
	v_pk_mul_f32 v[138:139], v[170:171], v[102:103]
	v_cvt_pk_bf16_f32 v122, v122, v123
	v_cvt_pk_bf16_f32 v123, v138, v139
	v_lshl_add_u64 v[138:139], v[172:173], 1, v[118:119]
	s_and_b64 vcc, exec, s[40:41]
	v_mov_b32_e32 v210, v122
	v_mov_b32_e32 v211, v123
	s_nop 1
	v_permlane16_swap_b32_e32 v208, v210
	v_permlane16_swap_b32_e32 v209, v211
	global_store_dwordx4 v[212:213], v[208:211], off
	s_cbranch_vccnz .LBB0_151
	v_mov_b32_e32 v117, v1
	v_lshl_add_u64 v[122:123], v[128:129], 0, v[116:117]
	v_cvt_pk_fp8_f32 v117, v104, v105
	v_mov_b32_e32 v104, v1
	v_mov_b32_e32 v105, v1
	v_cvt_pk_fp8_f32 v104, v106, v107
	v_cvt_pk_fp8_f32 v105, v100, v101
	v_mov_b32_e32 v106, v1
	v_add_co_u32_e32 v100, vcc, 0x4000, v122
	v_cvt_pk_fp8_f32 v106, v102, v103
	v_lshrrev_b32_e32 v102, 8, v117
	v_addc_co_u32_e32 v101, vcc, 0, v123, vcc
	global_store_byte v[100:101], v102, off
	v_add_co_u32_e32 v100, vcc, 0x8000, v122
	v_lshrrev_b32_e32 v102, 8, v104
	s_nop 0
	v_addc_co_u32_e32 v101, vcc, 0, v123, vcc
	global_store_byte v[100:101], v104, off
	v_add_co_u32_e32 v100, vcc, 0xc000, v122
	global_store_byte v[122:123], v117, off
	s_nop 0
	v_addc_co_u32_e32 v101, vcc, 0, v123, vcc
	global_store_byte v[100:101], v102, off
	v_add_co_u32_e32 v100, vcc, 0x40000, v122
	v_lshrrev_b32_e32 v102, 8, v105
	s_nop 0
	v_addc_co_u32_e32 v101, vcc, 0, v123, vcc
	global_store_byte v[100:101], v105, off
	v_add_co_u32_e32 v100, vcc, 0x44000, v122
	s_nop 1
	v_addc_co_u32_e32 v101, vcc, 0, v123, vcc
	global_store_byte v[100:101], v102, off
	v_add_co_u32_e32 v100, vcc, 0x48000, v122
	v_lshrrev_b32_e32 v102, 8, v106
	s_nop 0
	v_addc_co_u32_e32 v101, vcc, 0, v123, vcc
	global_store_byte v[100:101], v106, off
	v_add_co_u32_e32 v100, vcc, 0x4c000, v122
	s_nop 1
	v_addc_co_u32_e32 v101, vcc, 0, v123, vcc
	global_store_byte v[100:101], v102, off

; DI unsigned pack2(float a, float b) { f2_t v = {a, b}; return __builtin_bit_cast(unsigned, __builtin_convertvector(v, bf2_t)); }
;   DI void operator()(const f32x4 (&acc)[2][2][4][2], const pg8::Unit& u, int wr, int wc, int fr, int fq) const {
;     ...
;           const int row = u.pm * 256 + ai * 128 + wr * 64 + m * 16 + fr;
;           f32x4 x1 = acc[ai][bj][m][0], x2 = acc[ai][bj][m][1];
;           if (mode != 0) {
;             const float pos = (float)(row & (S - 1));
; #pragma unroll
;             for (int e = 0; e < 4; ++e) {
;               const float ang = __fmul_rn(pos, invv[e]);
;               float sn, cs; sincos_big(ang, sn, cs);
;               const float y1 = x1[e] * cs - x2[e] * sn, y2 = x2[e] * cs + x1[e] * sn;
;               x1[e] = y1; x2[e] = y2;
;             }
;           }
;           u16* dp = proj + (size_t)row * NPROJ;
;           *(uint2*)(dp + c1) = make_uint2(pack2(x1[0] * scale, x1[1] * scale), pack2(x1[2] * scale, x1[3] * scale));
;           *(uint2*)(dp + c2) = make_uint2(pack2(x2[0] * scale, x2[1] * scale), pack2(x2[2] * scale, x2[3] * scale));
;           if (gcol0 >= 512 && gcol0 < 768) {
;             const int hd = (gcol0 - 512) >> 6, d0 = (gcol0 & 63) + 4 * fq;
;             unsigned char* vp = vt8 + ((size_t)((row >> 14) * 4 + hd) * 64 + d0) * S + (row & (S - 1));
;             const int w1a = __builtin_amdgcn_cvt_pk_fp8_f32(x1[0], x1[1], 0, false), w1b = __builtin_amdgcn_cvt_pk_fp8_f32(x1[2], x1[3], 0, false);
;             const int w2a = __builtin_amdgcn_cvt_pk_fp8_f32(x2[0], x2[1], 0, false), w2b = __builtin_amdgcn_cvt_pk_fp8_f32(x2[2], x2[3], 0, false);
;             vp[0] = (unsigned char)(w1a & 0xff); vp[(size_t)S] = (unsigned char)((w1a >> 8) & 0xff); vp[(size_t)2 * S] = (unsigned char)(w1b & 0xff); vp[(size_t)3 * S] = (unsigned char)((w1b >> 8) & 0xff);
;             unsigned char* vq = vp + (size_t)16 * S;
;             vq[0] = (unsigned char)(w2a & 0xff); vq[(size_t)S] = (unsigned char)((w2a >> 8) & 0xff); vq[(size_t)2 * S] = (unsigned char)(w2b & 0xff); vq[(size_t)3 * S] = (unsigned char)((w2b >> 8) & 0xff);
;           }
.LBB0_153:
	v_mov_b64_e32 v[102:103], s[28:29]
	v_mad_i64_i32 v[102:103], s[16:17], v101, s9, v[102:103]
	v_pk_mul_f32 v[106:107], v[170:171], v[96:97]
	v_pk_mul_f32 v[122:123], v[170:171], v[98:99]
	v_cvt_pk_bf16_f32 v106, v106, v107
	v_cvt_pk_bf16_f32 v107, v122, v123
	v_lshl_add_u64 v[122:123], v[174:175], 1, v[102:103]
	v_bfe_u32 v222, v227, 4, 1
	v_mul_u32_u24_e32 v222, 0x17ff8, v222
	v_mov_b32_e32 v223, 0
	v_mov_b32_e32 v200, v106
	v_mov_b32_e32 v201, v107
	v_lshl_add_u64 v[204:205], v[122:123], 0, v[222:223]
	v_pk_mul_f32 v[106:107], v[170:171], v[92:93]
	v_pk_mul_f32 v[122:123], v[170:171], v[94:95]
	v_cvt_pk_bf16_f32 v106, v106, v107
	v_cvt_pk_bf16_f32 v107, v122, v123
	v_lshl_add_u64 v[122:123], v[172:173], 1, v[102:103]
	s_and_b64 vcc, exec, s[40:41]
	v_mov_b32_e32 v208, v106
	v_mov_b32_e32 v209, v107
	v_lshl_add_u64 v[212:213], v[122:123], 0, v[222:223]
	s_cbranch_vccnz .LBB0_155
	v_mov_b32_e32 v101, v1
	v_lshl_add_u64 v[106:107], v[128:129], 0, v[100:101]
	v_cvt_pk_fp8_f32 v101, v96, v97
	v_mov_b32_e32 v96, v1
	v_mov_b32_e32 v97, v1
	v_cvt_pk_fp8_f32 v96, v98, v99
	v_cvt_pk_fp8_f32 v97, v92, v93
	v_mov_b32_e32 v98, v1
	v_add_co_u32_e32 v92, vcc, 0x4000, v106
	v_cvt_pk_fp8_f32 v98, v94, v95
	v_lshrrev_b32_e32 v94, 8, v101
	v_addc_co_u32_e32 v93, vcc, 0, v107, vcc
	global_store_byte v[92:93], v94, off
	v_add_co_u32_e32 v92, vcc, 0x8000, v106
	v_lshrrev_b32_e32 v94, 8, v96
	s_nop 0
	v_addc_co_u32_e32 v93, vcc, 0, v107, vcc
	global_store_byte v[92:93], v96, off
	v_add_co_u32_e32 v92, vcc, 0xc000, v106
	global_store_byte v[106:107], v101, off
	s_nop 0
	v_addc_co_u32_e32 v93, vcc, 0, v107, vcc
	global_store_byte v[92:93], v94, off
	v_add_co_u32_e32 v92, vcc, 0x40000, v106
	v_lshrrev_b32_e32 v94, 8, v97
	s_nop 0
	v_addc_co_u32_e32 v93, vcc, 0, v107, vcc
	global_store_byte v[92:93], v97, off
	v_add_co_u32_e32 v92, vcc, 0x44000, v106
	s_nop 1
	v_addc_co_u32_e32 v93, vcc, 0, v107, vcc
	global_store_byte v[92:93], v94, off
	v_add_co_u32_e32 v92, vcc, 0x48000, v106
	v_lshrrev_b32_e32 v94, 8, v98
	s_nop 0
	v_addc_co_u32_e32 v93, vcc, 0, v107, vcc
	global_store_byte v[92:93], v98, off
	v_add_co_u32_e32 v92, vcc, 0x4c000, v106
	s_nop 1
	v_addc_co_u32_e32 v93, vcc, 0, v107, vcc
	global_store_byte v[92:93], v94, off

; DI unsigned pack2(float a, float b) { f2_t v = {a, b}; return __builtin_bit_cast(unsigned, __builtin_convertvector(v, bf2_t)); }
;   DI void operator()(const f32x4 (&acc)[2][2][4][2], const pg8::Unit& u, int wr, int wc, int fr, int fq) const {
;     ...
;           const int row = u.pm * 256 + ai * 128 + wr * 64 + m * 16 + fr;
;           f32x4 x1 = acc[ai][bj][m][0], x2 = acc[ai][bj][m][1];
;           if (mode != 0) {
;             const float pos = (float)(row & (S - 1));
; #pragma unroll
;             for (int e = 0; e < 4; ++e) {
;               const float ang = __fmul_rn(pos, invv[e]);
;               float sn, cs; sincos_big(ang, sn, cs);
;               const float y1 = x1[e] * cs - x2[e] * sn, y2 = x2[e] * cs + x1[e] * sn;
;               x1[e] = y1; x2[e] = y2;
;             }
;           }
;           u16* dp = proj + (size_t)row * NPROJ;
;           *(uint2*)(dp + c1) = make_uint2(pack2(x1[0] * scale, x1[1] * scale), pack2(x1[2] * scale, x1[3] * scale));
;           *(uint2*)(dp + c2) = make_uint2(pack2(x2[0] * scale, x2[1] * scale), pack2(x2[2] * scale, x2[3] * scale));
;           if (gcol0 >= 512 && gcol0 < 768) {
;             const int hd = (gcol0 - 512) >> 6, d0 = (gcol0 & 63) + 4 * fq;
;             unsigned char* vp = vt8 + ((size_t)((row >> 14) * 4 + hd) * 64 + d0) * S + (row & (S - 1));
;             const int w1a = __builtin_amdgcn_cvt_pk_fp8_f32(x1[0], x1[1], 0, false), w1b = __builtin_amdgcn_cvt_pk_fp8_f32(x1[2], x1[3], 0, false);
;             const int w2a = __builtin_amdgcn_cvt_pk_fp8_f32(x2[0], x2[1], 0, false), w2b = __builtin_amdgcn_cvt_pk_fp8_f32(x2[2], x2[3], 0, false);
;             vp[0] = (unsigned char)(w1a & 0xff); vp[(size_t)S] = (unsigned char)((w1a >> 8) & 0xff); vp[(size_t)2 * S] = (unsigned char)(w1b & 0xff); vp[(size_t)3 * S] = (unsigned char)((w1b >> 8) & 0xff);
;             unsigned char* vq = vp + (size_t)16 * S;
;             vq[0] = (unsigned char)(w2a & 0xff); vq[(size_t)S] = (unsigned char)((w2a >> 8) & 0xff); vq[(size_t)2 * S] = (unsigned char)(w2b & 0xff); vq[(size_t)3 * S] = (unsigned char)((w2b >> 8) & 0xff);
;           }
.LBB0_157:
	v_mov_b64_e32 v[94:95], s[28:29]
	v_mad_i64_i32 v[94:95], s[16:17], v93, s9, v[94:95]
	v_pk_mul_f32 v[98:99], v[170:171], v[88:89]
	v_pk_mul_f32 v[106:107], v[170:171], v[90:91]
	v_cvt_pk_bf16_f32 v98, v98, v99
	v_cvt_pk_bf16_f32 v99, v106, v107
	v_lshl_add_u64 v[106:107], v[174:175], 1, v[94:95]
	v_mov_b32_e32 v202, v98
	v_mov_b32_e32 v203, v99
	s_nop 1
	v_permlane16_swap_b32_e32 v200, v202
	v_permlane16_swap_b32_e32 v201, v203
	global_store_dwordx4 v[204:205], v[200:203], off
	v_pk_mul_f32 v[98:99], v[170:171], v[84:85]
	v_pk_mul_f32 v[106:107], v[170:171], v[86:87]
	v_cvt_pk_bf16_f32 v98, v98, v99
	v_cvt_pk_bf16_f32 v99, v106, v107
	v_lshl_add_u64 v[106:107], v[172:173], 1, v[94:95]
	s_and_b64 vcc, exec, s[40:41]
	v_mov_b32_e32 v210, v98
	v_mov_b32_e32 v211, v99
	s_nop 1
	v_permlane16_swap_b32_e32 v208, v210
	v_permlane16_swap_b32_e32 v209, v211
	global_store_dwordx4 v[212:213], v[208:211], off
	s_cbranch_vccnz .LBB0_159
	v_mov_b32_e32 v93, v1
	v_lshl_add_u64 v[98:99], v[128:129], 0, v[92:93]
	v_cvt_pk_fp8_f32 v93, v88, v89
	v_mov_b32_e32 v88, v1
	v_mov_b32_e32 v89, v1
	v_cvt_pk_fp8_f32 v88, v90, v91
	v_cvt_pk_fp8_f32 v89, v84, v85
	v_mov_b32_e32 v90, v1
	v_add_co_u32_e32 v84, vcc, 0x4000, v98
	v_cvt_pk_fp8_f32 v90, v86, v87
	v_lshrrev_b32_e32 v86, 8, v93
	v_addc_co_u32_e32 v85, vcc, 0, v99, vcc
	global_store_byte v[84:85], v86, off
	v_add_co_u32_e32 v84, vcc, 0x8000, v98
	v_lshrrev_b32_e32 v86, 8, v88
	s_nop 0
	v_addc_co_u32_e32 v85, vcc, 0, v99, vcc
	global_store_byte v[84:85], v88, off
	v_add_co_u32_e32 v84, vcc, 0xc000, v98
	global_store_byte v[98:99], v93, off
	s_nop 0
	v_addc_co_u32_e32 v85, vcc, 0, v99, vcc
	global_store_byte v[84:85], v86, off
	v_add_co_u32_e32 v84, vcc, 0x40000, v98
	v_lshrrev_b32_e32 v86, 8, v89
	s_nop 0
	v_addc_co_u32_e32 v85, vcc, 0, v99, vcc
	global_store_byte v[84:85], v89, off
	v_add_co_u32_e32 v84, vcc, 0x44000, v98
	s_nop 1
	v_addc_co_u32_e32 v85, vcc, 0, v99, vcc
	global_store_byte v[84:85], v86, off
	v_add_co_u32_e32 v84, vcc, 0x48000, v98
	v_lshrrev_b32_e32 v86, 8, v90
	s_nop 0
	v_addc_co_u32_e32 v85, vcc, 0, v99, vcc
	global_store_byte v[84:85], v90, off
	v_add_co_u32_e32 v84, vcc, 0x4c000, v98
	s_nop 1
	v_addc_co_u32_e32 v85, vcc, 0, v99, vcc
	global_store_byte v[84:85], v86, off

;   DI void operator()(const f32x4 (&acc)[2][2][4][2], const pg8::Unit& u, int wr, int wc, int fr, int fq) const {
;     ...
;       int c1, c2;
;       if (mode == 2) { const int hb = gcol0 & ~63, g = wc & 1; c1 = hb + 16 * g + 4 * fq; c2 = c1 + 32; }
;       else { c1 = gcol0 + 4 * fq; c2 = c1 + 16; }
; #pragma unroll
;       for (int ai = 0; ai < 2; ++ai)
; #pragma unroll
;         for (int m = 0; m < 4; ++m) {
;           const int row = u.pm * 256 + ai * 128 + wr * 64 + m * 16 + fr;
;           f32x4 x1 = acc[ai][bj][m][0], x2 = acc[ai][bj][m][1];
;           if (mode != 0) {
;             const float pos = (float)(row & (S - 1));
; #pragma unroll
;             for (int e = 0; e < 4; ++e) {
;               const float ang = __fmul_rn(pos, invv[e]);
;               float sn, cs; sincos_big(ang, sn, cs);
;               const float y1 = x1[e] * cs - x2[e] * sn, y2 = x2[e] * cs + x1[e] * sn;
;               x1[e] = y1; x2[e] = y2;
;             }
;           }
;           u16* dp = proj + (size_t)row * NPROJ;
;           *(uint2*)(dp + c1) = make_uint2(pack2(x1[0] * scale, x1[1] * scale), pack2(x1[2] * scale, x1[3] * scale));
;           *(uint2*)(dp + c2) = make_uint2(pack2(x2[0] * scale, x2[1] * scale), pack2(x2[2] * scale, x2[3] * scale));
;           if (gcol0 >= 512 && gcol0 < 768) {
;             const int hd = (gcol0 - 512) >> 6, d0 = (gcol0 & 63) + 4 * fq;
;             unsigned char* vp = vt8 + ((size_t)((row >> 14) * 4 + hd) * 64 + d0) * S + (row & (S - 1));
;             const int w1a = __builtin_amdgcn_cvt_pk_fp8_f32(x1[0], x1[1], 0, false), w1b = __builtin_amdgcn_cvt_pk_fp8_f32(x1[2], x1[3], 0, false);
;             const int w2a = __builtin_amdgcn_cvt_pk_fp8_f32(x2[0], x2[1], 0, false), w2b = __builtin_amdgcn_cvt_pk_fp8_f32(x2[2], x2[3], 0, false);
;             vp[0] = (unsigned char)(w1a & 0xff); vp[(size_t)S] = (unsigned char)((w1a >> 8) & 0xff); vp[(size_t)2 * S] = (unsigned char)(w1b & 0xff); vp[(size_t)3 * S] = (unsigned char)((w1b >> 8) & 0xff);
;             unsigned char* vq = vp + (size_t)16 * S;
;             vq[0] = (unsigned char)(w2a & 0xff); vq[(size_t)S] = (unsigned char)((w2a >> 8) & 0xff); vq[(size_t)2 * S] = (unsigned char)(w2b & 0xff); vq[(size_t)3 * S] = (unsigned char)((w2b >> 8) & 0xff);
;           }
.LBB0_171:
	s_and_b32 s6, s19, 0xffffffc0
	s_or_b32 s6, s6, s58
	s_and_b64 s[20:21], s[36:37], exec
	s_cselect_b32 s6, s6, s19
	s_cselect_b32 s20, 32, 16
	v_or_b32_e32 v88, s6, v180
	s_addk_i32 s19, 0xfe00
	v_ashrrev_i32_e32 v89, 31, v88
	s_lshr_b32 s6, s19, 6
	v_pk_mul_f32 v[90:91], v[84:85], v[80:81] op_sel_hi:[0,1]
	v_pk_mul_f32 v[106:107], v[84:85], v[82:83] op_sel_hi:[0,1]
	v_or_b32_e32 v86, s20, v88
	s_or_b32 s20, s7, s6
	v_cvt_pk_bf16_f32 v90, v90, v91
	v_cvt_pk_bf16_f32 v91, v106, v107
	v_lshl_add_u64 v[106:107], v[88:89], 1, v[168:169]
	v_ashrrev_i32_e32 v87, 31, v86
	s_ashr_i32 s21, s20, 31
	v_bfe_u32 v222, v227, 4, 1
	v_mul_u32_u24_e32 v222, 0x17ff8, v222
	v_mov_b32_e32 v223, 0
	v_mov_b32_e32 v200, v90
	v_mov_b32_e32 v201, v91
	v_lshl_add_u64 v[204:205], v[106:107], 0, v[222:223]
	v_pk_mul_f32 v[90:91], v[84:85], v[76:77] op_sel_hi:[0,1]
	v_pk_mul_f32 v[106:107], v[84:85], v[78:79] op_sel_hi:[0,1]
	s_lshl_b64 s[20:21], s[20:21], 20
	v_cvt_pk_bf16_f32 v90, v90, v91
	v_cvt_pk_bf16_f32 v91, v106, v107
	v_lshl_add_u64 v[106:107], v[86:87], 1, v[168:169]
	v_mov_b32_e32 v208, v90
	v_mov_b32_e32 v209, v91
	v_lshl_add_u64 v[212:213], v[106:107], 0, v[222:223]
	s_and_b64 vcc, exec, s[40:41]
	v_lshl_add_u64 v[90:91], v[162:163], 0, s[20:21]
	s_cbranch_vccnz .LBB0_173
	v_lshl_add_u64 v[106:107], v[90:91], 0, v[0:1]
	v_mov_b32_e32 v0, v1
	v_cvt_pk_fp8_f32 v0, v80, v81
	v_mov_b32_e32 v80, v1
	v_mov_b32_e32 v81, v1
	v_cvt_pk_fp8_f32 v80, v82, v83
	v_cvt_pk_fp8_f32 v81, v76, v77
	v_add_co_u32_e32 v76, vcc, 0x4000, v106
	global_store_byte v[106:107], v0, off
	v_lshrrev_b32_e32 v0, 8, v0
	v_addc_co_u32_e32 v77, vcc, 0, v107, vcc
	global_store_byte v[76:77], v0, off
	v_add_co_u32_e32 v76, vcc, 0x8000, v106
	v_lshrrev_b32_e32 v0, 8, v80
	s_nop 0
	v_addc_co_u32_e32 v77, vcc, 0, v107, vcc
	global_store_byte v[76:77], v80, off
	v_add_co_u32_e32 v76, vcc, 0xc000, v106
	v_mov_b32_e32 v82, v1
	s_nop 0
	v_addc_co_u32_e32 v77, vcc, 0, v107, vcc
	global_store_byte v[76:77], v0, off
	v_add_co_u32_e32 v76, vcc, 0x40000, v106
	v_cvt_pk_fp8_f32 v82, v78, v79
	s_nop 0
	v_addc_co_u32_e32 v77, vcc, 0, v107, vcc
	global_store_byte v[76:77], v81, off
	v_add_co_u32_e32 v76, vcc, 0x44000, v106
	v_lshrrev_b32_e32 v0, 8, v81
	s_nop 0
	v_addc_co_u32_e32 v77, vcc, 0, v107, vcc
	global_store_byte v[76:77], v0, off
	v_add_co_u32_e32 v76, vcc, 0x48000, v106
	v_lshrrev_b32_e32 v0, 8, v82
	s_nop 0
	v_addc_co_u32_e32 v77, vcc, 0, v107, vcc
	global_store_byte v[76:77], v82, off
	v_add_co_u32_e32 v76, vcc, 0x4c000, v106
	s_nop 1
	v_addc_co_u32_e32 v77, vcc, 0, v107, vcc
	global_store_byte v[76:77], v0, off

; DI unsigned pack2(float a, float b) { f2_t v = {a, b}; return __builtin_bit_cast(unsigned, __builtin_convertvector(v, bf2_t)); }
;   DI void operator()(const f32x4 (&acc)[2][2][4][2], const pg8::Unit& u, int wr, int wc, int fr, int fq) const {
;     ...
;           const int row = u.pm * 256 + ai * 128 + wr * 64 + m * 16 + fr;
;           f32x4 x1 = acc[ai][bj][m][0], x2 = acc[ai][bj][m][1];
;           if (mode != 0) {
;             const float pos = (float)(row & (S - 1));
; #pragma unroll
;             for (int e = 0; e < 4; ++e) {
;               const float ang = __fmul_rn(pos, invv[e]);
;               float sn, cs; sincos_big(ang, sn, cs);
;               const float y1 = x1[e] * cs - x2[e] * sn, y2 = x2[e] * cs + x1[e] * sn;
;               x1[e] = y1; x2[e] = y2;
;             }
;           }
;           u16* dp = proj + (size_t)row * NPROJ;
;           *(uint2*)(dp + c1) = make_uint2(pack2(x1[0] * scale, x1[1] * scale), pack2(x1[2] * scale, x1[3] * scale));
;           *(uint2*)(dp + c2) = make_uint2(pack2(x2[0] * scale, x2[1] * scale), pack2(x2[2] * scale, x2[3] * scale));
;           if (gcol0 >= 512 && gcol0 < 768) {
;             const int hd = (gcol0 - 512) >> 6, d0 = (gcol0 & 63) + 4 * fq;
;             unsigned char* vp = vt8 + ((size_t)((row >> 14) * 4 + hd) * 64 + d0) * S + (row & (S - 1));
;             const int w1a = __builtin_amdgcn_cvt_pk_fp8_f32(x1[0], x1[1], 0, false), w1b = __builtin_amdgcn_cvt_pk_fp8_f32(x1[2], x1[3], 0, false);
;             const int w2a = __builtin_amdgcn_cvt_pk_fp8_f32(x2[0], x2[1], 0, false), w2b = __builtin_amdgcn_cvt_pk_fp8_f32(x2[2], x2[3], 0, false);
;             vp[0] = (unsigned char)(w1a & 0xff); vp[(size_t)S] = (unsigned char)((w1a >> 8) & 0xff); vp[(size_t)2 * S] = (unsigned char)(w1b & 0xff); vp[(size_t)3 * S] = (unsigned char)((w1b >> 8) & 0xff);
;             unsigned char* vq = vp + (size_t)16 * S;
;             vq[0] = (unsigned char)(w2a & 0xff); vq[(size_t)S] = (unsigned char)((w2a >> 8) & 0xff); vq[(size_t)2 * S] = (unsigned char)(w2b & 0xff); vq[(size_t)3 * S] = (unsigned char)((w2b >> 8) & 0xff);
;           }
.LBB0_175:
	v_mov_b32_e32 v85, v84
	v_pk_mul_f32 v[76:77], v[84:85], v[72:73]
	v_pk_mul_f32 v[78:79], v[84:85], v[74:75]
	v_cvt_pk_bf16_f32 v76, v76, v77
	v_cvt_pk_bf16_f32 v77, v78, v79
	v_lshl_add_u64 v[78:79], v[88:89], 1, v[150:151]
	v_mov_b32_e32 v202, v76
	v_mov_b32_e32 v203, v77
	s_nop 1
	v_permlane16_swap_b32_e32 v200, v202
	v_permlane16_swap_b32_e32 v201, v203
	global_store_dwordx4 v[204:205], v[200:203], off
	v_pk_mul_f32 v[76:77], v[84:85], v[68:69]
	v_pk_mul_f32 v[78:79], v[84:85], v[70:71]
	v_cvt_pk_bf16_f32 v76, v76, v77
	v_cvt_pk_bf16_f32 v77, v78, v79
	v_lshl_add_u64 v[78:79], v[86:87], 1, v[150:151]
	s_and_b64 vcc, exec, s[40:41]
	v_mov_b32_e32 v210, v76
	v_mov_b32_e32 v211, v77
	s_nop 1
	v_permlane16_swap_b32_e32 v208, v210
	v_permlane16_swap_b32_e32 v209, v211
	global_store_dwordx4 v[212:213], v[208:211], off
	s_cbranch_vccnz .LBB0_177
	v_mov_b32_e32 v0, v1
	v_cvt_pk_fp8_f32 v0, v72, v73
	v_mov_b32_e32 v149, v1
	v_lshl_add_u64 v[76:77], v[90:91], 0, v[148:149]
	v_mov_b32_e32 v72, v1
	v_mov_b32_e32 v73, v1
	v_cvt_pk_fp8_f32 v72, v74, v75
	v_cvt_pk_fp8_f32 v73, v68, v69
	v_add_co_u32_e32 v68, vcc, 0x4000, v76
	global_store_byte v[76:77], v0, off
	v_lshrrev_b32_e32 v0, 8, v0
	v_addc_co_u32_e32 v69, vcc, 0, v77, vcc
	global_store_byte v[68:69], v0, off
	v_add_co_u32_e32 v68, vcc, 0x8000, v76
	v_lshrrev_b32_e32 v0, 8, v72
	s_nop 0
	v_addc_co_u32_e32 v69, vcc, 0, v77, vcc
	global_store_byte v[68:69], v72, off
	v_add_co_u32_e32 v68, vcc, 0xc000, v76
	v_mov_b32_e32 v74, v1
	s_nop 0
	v_addc_co_u32_e32 v69, vcc, 0, v77, vcc
	global_store_byte v[68:69], v0, off
	v_add_co_u32_e32 v68, vcc, 0x40000, v76
	v_cvt_pk_fp8_f32 v74, v70, v71
	s_nop 0
	v_addc_co_u32_e32 v69, vcc, 0, v77, vcc
	global_store_byte v[68:69], v73, off
	v_add_co_u32_e32 v68, vcc, 0x44000, v76
	v_lshrrev_b32_e32 v0, 8, v73
	s_nop 0
	v_addc_co_u32_e32 v69, vcc, 0, v77, vcc
	global_store_byte v[68:69], v0, off
	v_add_co_u32_e32 v68, vcc, 0x48000, v76
	v_lshrrev_b32_e32 v0, 8, v74
	s_nop 0
	v_addc_co_u32_e32 v69, vcc, 0, v77, vcc
	global_store_byte v[68:69], v74, off
	v_add_co_u32_e32 v68, vcc, 0x4c000, v76
	s_nop 1
	v_addc_co_u32_e32 v69, vcc, 0, v77, vcc
	global_store_byte v[68:69], v0, off

; DI unsigned pack2(float a, float b) { f2_t v = {a, b}; return __builtin_bit_cast(unsigned, __builtin_convertvector(v, bf2_t)); }
;   DI void operator()(const f32x4 (&acc)[2][2][4][2], const pg8::Unit& u, int wr, int wc, int fr, int fq) const {
;     ...
;           const int row = u.pm * 256 + ai * 128 + wr * 64 + m * 16 + fr;
;           f32x4 x1 = acc[ai][bj][m][0], x2 = acc[ai][bj][m][1];
;           if (mode != 0) {
;             const float pos = (float)(row & (S - 1));
; #pragma unroll
;             for (int e = 0; e < 4; ++e) {
;               const float ang = __fmul_rn(pos, invv[e]);
;               float sn, cs; sincos_big(ang, sn, cs);
;               const float y1 = x1[e] * cs - x2[e] * sn, y2 = x2[e] * cs + x1[e] * sn;
;               x1[e] = y1; x2[e] = y2;
;             }
;           }
;           u16* dp = proj + (size_t)row * NPROJ;
;           *(uint2*)(dp + c1) = make_uint2(pack2(x1[0] * scale, x1[1] * scale), pack2(x1[2] * scale, x1[3] * scale));
;           *(uint2*)(dp + c2) = make_uint2(pack2(x2[0] * scale, x2[1] * scale), pack2(x2[2] * scale, x2[3] * scale));
;           if (gcol0 >= 512 && gcol0 < 768) {
;             const int hd = (gcol0 - 512) >> 6, d0 = (gcol0 & 63) + 4 * fq;
;             unsigned char* vp = vt8 + ((size_t)((row >> 14) * 4 + hd) * 64 + d0) * S + (row & (S - 1));
;             const int w1a = __builtin_amdgcn_cvt_pk_fp8_f32(x1[0], x1[1], 0, false), w1b = __builtin_amdgcn_cvt_pk_fp8_f32(x1[2], x1[3], 0, false);
;             const int w2a = __builtin_amdgcn_cvt_pk_fp8_f32(x2[0], x2[1], 0, false), w2b = __builtin_amdgcn_cvt_pk_fp8_f32(x2[2], x2[3], 0, false);
;             vp[0] = (unsigned char)(w1a & 0xff); vp[(size_t)S] = (unsigned char)((w1a >> 8) & 0xff); vp[(size_t)2 * S] = (unsigned char)(w1b & 0xff); vp[(size_t)3 * S] = (unsigned char)((w1b >> 8) & 0xff);
;             unsigned char* vq = vp + (size_t)16 * S;
;             vq[0] = (unsigned char)(w2a & 0xff); vq[(size_t)S] = (unsigned char)((w2a >> 8) & 0xff); vq[(size_t)2 * S] = (unsigned char)(w2b & 0xff); vq[(size_t)3 * S] = (unsigned char)((w2b >> 8) & 0xff);
;           }
.LBB0_179:
	v_pk_mul_f32 v[68:69], v[84:85], v[64:65]
	v_pk_mul_f32 v[70:71], v[84:85], v[66:67]
	v_cvt_pk_bf16_f32 v68, v68, v69
	v_cvt_pk_bf16_f32 v69, v70, v71
	v_lshl_add_u64 v[70:71], v[88:89], 1, v[142:143]
	v_bfe_u32 v222, v227, 4, 1
	v_mul_u32_u24_e32 v222, 0x17ff8, v222
	v_mov_b32_e32 v223, 0
	v_mov_b32_e32 v200, v68
	v_mov_b32_e32 v201, v69
	v_lshl_add_u64 v[204:205], v[70:71], 0, v[222:223]
	v_pk_mul_f32 v[68:69], v[84:85], v[60:61]
	v_pk_mul_f32 v[70:71], v[84:85], v[62:63]
	v_cvt_pk_bf16_f32 v68, v68, v69
	v_cvt_pk_bf16_f32 v69, v70, v71
	v_lshl_add_u64 v[70:71], v[86:87], 1, v[142:143]
	s_and_b64 vcc, exec, s[40:41]
	v_mov_b32_e32 v208, v68
	v_mov_b32_e32 v209, v69
	v_lshl_add_u64 v[212:213], v[70:71], 0, v[222:223]
	s_cbranch_vccnz .LBB0_181
	v_mov_b32_e32 v0, v1
	v_cvt_pk_fp8_f32 v0, v64, v65
	v_mov_b32_e32 v141, v1
	v_lshl_add_u64 v[68:69], v[90:91], 0, v[140:141]
	v_mov_b32_e32 v64, v1
	v_mov_b32_e32 v65, v1
	v_cvt_pk_fp8_f32 v64, v66, v67
	v_cvt_pk_fp8_f32 v65, v60, v61
	v_add_co_u32_e32 v60, vcc, 0x4000, v68
	global_store_byte v[68:69], v0, off
	v_lshrrev_b32_e32 v0, 8, v0
	v_addc_co_u32_e32 v61, vcc, 0, v69, vcc
	global_store_byte v[60:61], v0, off
	v_add_co_u32_e32 v60, vcc, 0x8000, v68
	v_lshrrev_b32_e32 v0, 8, v64
	s_nop 0
	v_addc_co_u32_e32 v61, vcc, 0, v69, vcc
	global_store_byte v[60:61], v64, off
	v_add_co_u32_e32 v60, vcc, 0xc000, v68
	v_mov_b32_e32 v66, v1
	s_nop 0
	v_addc_co_u32_e32 v61, vcc, 0, v69, vcc
	global_store_byte v[60:61], v0, off
	v_add_co_u32_e32 v60, vcc, 0x40000, v68
	v_cvt_pk_fp8_f32 v66, v62, v63
	s_nop 0
	v_addc_co_u32_e32 v61, vcc, 0, v69, vcc
	global_store_byte v[60:61], v65, off
	v_add_co_u32_e32 v60, vcc, 0x44000, v68
	v_lshrrev_b32_e32 v0, 8, v65
	s_nop 0
	v_addc_co_u32_e32 v61, vcc, 0, v69, vcc
	global_store_byte v[60:61], v0, off
	v_add_co_u32_e32 v60, vcc, 0x48000, v68
	v_lshrrev_b32_e32 v0, 8, v66
	s_nop 0
	v_addc_co_u32_e32 v61, vcc, 0, v69, vcc
	global_store_byte v[60:61], v66, off
	v_add_co_u32_e32 v60, vcc, 0x4c000, v68
	s_nop 1
	v_addc_co_u32_e32 v61, vcc, 0, v69, vcc
	global_store_byte v[60:61], v0, off

; DI unsigned pack2(float a, float b) { f2_t v = {a, b}; return __builtin_bit_cast(unsigned, __builtin_convertvector(v, bf2_t)); }
;   DI void operator()(const f32x4 (&acc)[2][2][4][2], const pg8::Unit& u, int wr, int wc, int fr, int fq) const {
;     ...
;           const int row = u.pm * 256 + ai * 128 + wr * 64 + m * 16 + fr;
;           f32x4 x1 = acc[ai][bj][m][0], x2 = acc[ai][bj][m][1];
;           if (mode != 0) {
;             const float pos = (float)(row & (S - 1));
; #pragma unroll
;             for (int e = 0; e < 4; ++e) {
;               const float ang = __fmul_rn(pos, invv[e]);
;               float sn, cs; sincos_big(ang, sn, cs);
;               const float y1 = x1[e] * cs - x2[e] * sn, y2 = x2[e] * cs + x1[e] * sn;
;               x1[e] = y1; x2[e] = y2;
;             }
;           }
;           u16* dp = proj + (size_t)row * NPROJ;
;           *(uint2*)(dp + c1) = make_uint2(pack2(x1[0] * scale, x1[1] * scale), pack2(x1[2] * scale, x1[3] * scale));
;           *(uint2*)(dp + c2) = make_uint2(pack2(x2[0] * scale, x2[1] * scale), pack2(x2[2] * scale, x2[3] * scale));
;           if (gcol0 >= 512 && gcol0 < 768) {
;             const int hd = (gcol0 - 512) >> 6, d0 = (gcol0 & 63) + 4 * fq;
;             unsigned char* vp = vt8 + ((size_t)((row >> 14) * 4 + hd) * 64 + d0) * S + (row & (S - 1));
;             const int w1a = __builtin_amdgcn_cvt_pk_fp8_f32(x1[0], x1[1], 0, false), w1b = __builtin_amdgcn_cvt_pk_fp8_f32(x1[2], x1[3], 0, false);
;             const int w2a = __builtin_amdgcn_cvt_pk_fp8_f32(x2[0], x2[1], 0, false), w2b = __builtin_amdgcn_cvt_pk_fp8_f32(x2[2], x2[3], 0, false);
;             vp[0] = (unsigned char)(w1a & 0xff); vp[(size_t)S] = (unsigned char)((w1a >> 8) & 0xff); vp[(size_t)2 * S] = (unsigned char)(w1b & 0xff); vp[(size_t)3 * S] = (unsigned char)((w1b >> 8) & 0xff);
;             unsigned char* vq = vp + (size_t)16 * S;
;             vq[0] = (unsigned char)(w2a & 0xff); vq[(size_t)S] = (unsigned char)((w2a >> 8) & 0xff); vq[(size_t)2 * S] = (unsigned char)(w2b & 0xff); vq[(size_t)3 * S] = (unsigned char)((w2b >> 8) & 0xff);
;           }
.LBB0_183:
	v_pk_mul_f32 v[60:61], v[84:85], v[56:57]
	v_pk_mul_f32 v[62:63], v[84:85], v[58:59]
	v_cvt_pk_bf16_f32 v60, v60, v61
	v_cvt_pk_bf16_f32 v61, v62, v63
	v_lshl_add_u64 v[62:63], v[88:89], 1, v[134:135]
	v_mov_b32_e32 v202, v60
	v_mov_b32_e32 v203, v61
	s_nop 1
	v_permlane16_swap_b32_e32 v200, v202
	v_permlane16_swap_b32_e32 v201, v203
	global_store_dwordx4 v[204:205], v[200:203], off
	v_pk_mul_f32 v[60:61], v[84:85], v[52:53]
	v_pk_mul_f32 v[62:63], v[84:85], v[54:55]
	v_cvt_pk_bf16_f32 v60, v60, v61
	v_cvt_pk_bf16_f32 v61, v62, v63
	v_lshl_add_u64 v[62:63], v[86:87], 1, v[134:135]
	s_and_b64 vcc, exec, s[40:41]
	v_mov_b32_e32 v210, v60
	v_mov_b32_e32 v211, v61
	s_nop 1
	v_permlane16_swap_b32_e32 v208, v210
	v_permlane16_swap_b32_e32 v209, v211
	global_store_dwordx4 v[212:213], v[208:211], off
	s_cbranch_vccnz .LBB0_185
	v_mov_b32_e32 v0, v1
	v_cvt_pk_fp8_f32 v0, v56, v57
	v_mov_b32_e32 v133, v1
	v_lshl_add_u64 v[60:61], v[90:91], 0, v[132:133]
	v_mov_b32_e32 v56, v1
	v_mov_b32_e32 v57, v1
	v_cvt_pk_fp8_f32 v56, v58, v59
	v_cvt_pk_fp8_f32 v57, v52, v53
	v_add_co_u32_e32 v52, vcc, 0x4000, v60
	global_store_byte v[60:61], v0, off
	v_lshrrev_b32_e32 v0, 8, v0
	v_addc_co_u32_e32 v53, vcc, 0, v61, vcc
	global_store_byte v[52:53], v0, off
	v_add_co_u32_e32 v52, vcc, 0x8000, v60
	v_lshrrev_b32_e32 v0, 8, v56
	s_nop 0
	v_addc_co_u32_e32 v53, vcc, 0, v61, vcc
	global_store_byte v[52:53], v56, off
	v_add_co_u32_e32 v52, vcc, 0xc000, v60
	v_mov_b32_e32 v58, v1
	s_nop 0
	v_addc_co_u32_e32 v53, vcc, 0, v61, vcc
	global_store_byte v[52:53], v0, off
	v_add_co_u32_e32 v52, vcc, 0x40000, v60
	v_cvt_pk_fp8_f32 v58, v54, v55
	s_nop 0
	v_addc_co_u32_e32 v53, vcc, 0, v61, vcc
	global_store_byte v[52:53], v57, off
	v_add_co_u32_e32 v52, vcc, 0x44000, v60
	v_lshrrev_b32_e32 v0, 8, v57
	s_nop 0
	v_addc_co_u32_e32 v53, vcc, 0, v61, vcc
	global_store_byte v[52:53], v0, off
	v_add_co_u32_e32 v52, vcc, 0x48000, v60
	v_lshrrev_b32_e32 v0, 8, v58
	s_nop 0
	v_addc_co_u32_e32 v53, vcc, 0, v61, vcc
	global_store_byte v[52:53], v58, off
	v_add_co_u32_e32 v52, vcc, 0x4c000, v60
	s_nop 1
	v_addc_co_u32_e32 v53, vcc, 0, v61, vcc
	global_store_byte v[52:53], v0, off

; DI unsigned pack2(float a, float b) { f2_t v = {a, b}; return __builtin_bit_cast(unsigned, __builtin_convertvector(v, bf2_t)); }
;   DI void operator()(const f32x4 (&acc)[2][2][4][2], const pg8::Unit& u, int wr, int wc, int fr, int fq) const {
;     ...
;           const int row = u.pm * 256 + ai * 128 + wr * 64 + m * 16 + fr;
;           f32x4 x1 = acc[ai][bj][m][0], x2 = acc[ai][bj][m][1];
;           if (mode != 0) {
;             const float pos = (float)(row & (S - 1));
; #pragma unroll
;             for (int e = 0; e < 4; ++e) {
;               const float ang = __fmul_rn(pos, invv[e]);
;               float sn, cs; sincos_big(ang, sn, cs);
;               const float y1 = x1[e] * cs - x2[e] * sn, y2 = x2[e] * cs + x1[e] * sn;
;               x1[e] = y1; x2[e] = y2;
;             }
;           }
;           u16* dp = proj + (size_t)row * NPROJ;
;           *(uint2*)(dp + c1) = make_uint2(pack2(x1[0] * scale, x1[1] * scale), pack2(x1[2] * scale, x1[3] * scale));
;           *(uint2*)(dp + c2) = make_uint2(pack2(x2[0] * scale, x2[1] * scale), pack2(x2[2] * scale, x2[3] * scale));
;           if (gcol0 >= 512 && gcol0 < 768) {
;             const int hd = (gcol0 - 512) >> 6, d0 = (gcol0 & 63) + 4 * fq;
;             unsigned char* vp = vt8 + ((size_t)((row >> 14) * 4 + hd) * 64 + d0) * S + (row & (S - 1));
;             const int w1a = __builtin_amdgcn_cvt_pk_fp8_f32(x1[0], x1[1], 0, false), w1b = __builtin_amdgcn_cvt_pk_fp8_f32(x1[2], x1[3], 0, false);
;             const int w2a = __builtin_amdgcn_cvt_pk_fp8_f32(x2[0], x2[1], 0, false), w2b = __builtin_amdgcn_cvt_pk_fp8_f32(x2[2], x2[3], 0, false);
;             vp[0] = (unsigned char)(w1a & 0xff); vp[(size_t)S] = (unsigned char)((w1a >> 8) & 0xff); vp[(size_t)2 * S] = (unsigned char)(w1b & 0xff); vp[(size_t)3 * S] = (unsigned char)((w1b >> 8) & 0xff);
;             unsigned char* vq = vp + (size_t)16 * S;
;             vq[0] = (unsigned char)(w2a & 0xff); vq[(size_t)S] = (unsigned char)((w2a >> 8) & 0xff); vq[(size_t)2 * S] = (unsigned char)(w2b & 0xff); vq[(size_t)3 * S] = (unsigned char)((w2b >> 8) & 0xff);
;           }
.LBB0_187:
	v_pk_mul_f32 v[52:53], v[84:85], v[48:49]
	v_pk_mul_f32 v[54:55], v[84:85], v[50:51]
	s_or_b32 s6, s18, s6
	v_cvt_pk_bf16_f32 v52, v52, v53
	v_cvt_pk_bf16_f32 v53, v54, v55
	v_lshl_add_u64 v[54:55], v[88:89], 1, v[126:127]
	s_ashr_i32 s7, s6, 31
	v_bfe_u32 v222, v227, 4, 1
	v_mul_u32_u24_e32 v222, 0x17ff8, v222
	v_mov_b32_e32 v223, 0
	v_mov_b32_e32 v200, v52
	v_mov_b32_e32 v201, v53
	v_lshl_add_u64 v[204:205], v[54:55], 0, v[222:223]
	v_pk_mul_f32 v[52:53], v[84:85], v[44:45]
	v_pk_mul_f32 v[54:55], v[84:85], v[46:47]
	s_lshl_b64 s[6:7], s[6:7], 20
	v_cvt_pk_bf16_f32 v52, v52, v53
	v_cvt_pk_bf16_f32 v53, v54, v55
	v_lshl_add_u64 v[54:55], v[86:87], 1, v[126:127]
	v_mov_b32_e32 v208, v52
	v_mov_b32_e32 v209, v53
	v_lshl_add_u64 v[212:213], v[54:55], 0, v[222:223]
	s_and_b64 vcc, exec, s[40:41]
	v_lshl_add_u64 v[52:53], v[162:163], 0, s[6:7]
	s_cbranch_vccnz .LBB0_189
	v_mov_b32_e32 v0, v1
	v_cvt_pk_fp8_f32 v0, v48, v49
	v_mov_b32_e32 v125, v1
	v_lshl_add_u64 v[54:55], v[52:53], 0, v[124:125]
	v_mov_b32_e32 v48, v1
	v_mov_b32_e32 v49, v1
	v_cvt_pk_fp8_f32 v48, v50, v51
	v_cvt_pk_fp8_f32 v49, v44, v45
	v_add_co_u32_e32 v44, vcc, 0x4000, v54
	global_store_byte v[54:55], v0, off
	v_lshrrev_b32_e32 v0, 8, v0
	v_addc_co_u32_e32 v45, vcc, 0, v55, vcc
	global_store_byte v[44:45], v0, off
	v_add_co_u32_e32 v44, vcc, 0x8000, v54
	v_lshrrev_b32_e32 v0, 8, v48
	s_nop 0
	v_addc_co_u32_e32 v45, vcc, 0, v55, vcc
	global_store_byte v[44:45], v48, off
	v_add_co_u32_e32 v44, vcc, 0xc000, v54
	v_mov_b32_e32 v50, v1
	s_nop 0
	v_addc_co_u32_e32 v45, vcc, 0, v55, vcc
	global_store_byte v[44:45], v0, off
	v_add_co_u32_e32 v44, vcc, 0x40000, v54
	v_cvt_pk_fp8_f32 v50, v46, v47
	s_nop 0
	v_addc_co_u32_e32 v45, vcc, 0, v55, vcc
	global_store_byte v[44:45], v49, off
	v_add_co_u32_e32 v44, vcc, 0x44000, v54
	v_lshrrev_b32_e32 v0, 8, v49
	s_nop 0
	v_addc_co_u32_e32 v45, vcc, 0, v55, vcc
	global_store_byte v[44:45], v0, off
	v_add_co_u32_e32 v44, vcc, 0x48000, v54
	v_lshrrev_b32_e32 v0, 8, v50
	s_nop 0
	v_addc_co_u32_e32 v45, vcc, 0, v55, vcc
	global_store_byte v[44:45], v50, off
	v_add_co_u32_e32 v44, vcc, 0x4c000, v54
	s_nop 1
	v_addc_co_u32_e32 v45, vcc, 0, v55, vcc
	global_store_byte v[44:45], v0, off

; DI unsigned pack2(float a, float b) { f2_t v = {a, b}; return __builtin_bit_cast(unsigned, __builtin_convertvector(v, bf2_t)); }
;   DI void operator()(const f32x4 (&acc)[2][2][4][2], const pg8::Unit& u, int wr, int wc, int fr, int fq) const {
;     ...
;           const int row = u.pm * 256 + ai * 128 + wr * 64 + m * 16 + fr;
;           f32x4 x1 = acc[ai][bj][m][0], x2 = acc[ai][bj][m][1];
;           if (mode != 0) {
;             const float pos = (float)(row & (S - 1));
; #pragma unroll
;             for (int e = 0; e < 4; ++e) {
;               const float ang = __fmul_rn(pos, invv[e]);
;               float sn, cs; sincos_big(ang, sn, cs);
;               const float y1 = x1[e] * cs - x2[e] * sn, y2 = x2[e] * cs + x1[e] * sn;
;               x1[e] = y1; x2[e] = y2;
;             }
;           }
;           u16* dp = proj + (size_t)row * NPROJ;
;           *(uint2*)(dp + c1) = make_uint2(pack2(x1[0] * scale, x1[1] * scale), pack2(x1[2] * scale, x1[3] * scale));
;           *(uint2*)(dp + c2) = make_uint2(pack2(x2[0] * scale, x2[1] * scale), pack2(x2[2] * scale, x2[3] * scale));
;           if (gcol0 >= 512 && gcol0 < 768) {
;             const int hd = (gcol0 - 512) >> 6, d0 = (gcol0 & 63) + 4 * fq;
;             unsigned char* vp = vt8 + ((size_t)((row >> 14) * 4 + hd) * 64 + d0) * S + (row & (S - 1));
;             const int w1a = __builtin_amdgcn_cvt_pk_fp8_f32(x1[0], x1[1], 0, false), w1b = __builtin_amdgcn_cvt_pk_fp8_f32(x1[2], x1[3], 0, false);
;             const int w2a = __builtin_amdgcn_cvt_pk_fp8_f32(x2[0], x2[1], 0, false), w2b = __builtin_amdgcn_cvt_pk_fp8_f32(x2[2], x2[3], 0, false);
;             vp[0] = (unsigned char)(w1a & 0xff); vp[(size_t)S] = (unsigned char)((w1a >> 8) & 0xff); vp[(size_t)2 * S] = (unsigned char)(w1b & 0xff); vp[(size_t)3 * S] = (unsigned char)((w1b >> 8) & 0xff);
;             unsigned char* vq = vp + (size_t)16 * S;
;             vq[0] = (unsigned char)(w2a & 0xff); vq[(size_t)S] = (unsigned char)((w2a >> 8) & 0xff); vq[(size_t)2 * S] = (unsigned char)(w2b & 0xff); vq[(size_t)3 * S] = (unsigned char)((w2b >> 8) & 0xff);
;           }
.LBB0_191:
	v_pk_mul_f32 v[44:45], v[84:85], v[40:41]
	v_pk_mul_f32 v[46:47], v[84:85], v[42:43]
	v_cvt_pk_bf16_f32 v44, v44, v45
	v_cvt_pk_bf16_f32 v45, v46, v47
	v_lshl_add_u64 v[46:47], v[88:89], 1, v[118:119]
	v_mov_b32_e32 v202, v44
	v_mov_b32_e32 v203, v45
	s_nop 1
	v_permlane16_swap_b32_e32 v200, v202
	v_permlane16_swap_b32_e32 v201, v203
	global_store_dwordx4 v[204:205], v[200:203], off
	v_pk_mul_f32 v[44:45], v[84:85], v[36:37]
	v_pk_mul_f32 v[46:47], v[84:85], v[38:39]
	v_cvt_pk_bf16_f32 v44, v44, v45
	v_cvt_pk_bf16_f32 v45, v46, v47
	v_lshl_add_u64 v[46:47], v[86:87], 1, v[118:119]
	s_and_b64 vcc, exec, s[40:41]
	v_mov_b32_e32 v210, v44
	v_mov_b32_e32 v211, v45
	s_nop 1
	v_permlane16_swap_b32_e32 v208, v210
	v_permlane16_swap_b32_e32 v209, v211
	global_store_dwordx4 v[212:213], v[208:211], off
	s_cbranch_vccnz .LBB0_193
	v_mov_b32_e32 v0, v1
	v_cvt_pk_fp8_f32 v0, v40, v41
	v_mov_b32_e32 v117, v1
	v_lshl_add_u64 v[44:45], v[52:53], 0, v[116:117]
	v_mov_b32_e32 v40, v1
	v_mov_b32_e32 v41, v1
	v_cvt_pk_fp8_f32 v40, v42, v43
	v_cvt_pk_fp8_f32 v41, v36, v37
	v_add_co_u32_e32 v36, vcc, 0x4000, v44
	global_store_byte v[44:45], v0, off
	v_lshrrev_b32_e32 v0, 8, v0
	v_addc_co_u32_e32 v37, vcc, 0, v45, vcc
	global_store_byte v[36:37], v0, off
	v_add_co_u32_e32 v36, vcc, 0x8000, v44
	v_lshrrev_b32_e32 v0, 8, v40
	s_nop 0
	v_addc_co_u32_e32 v37, vcc, 0, v45, vcc
	global_store_byte v[36:37], v40, off
	v_add_co_u32_e32 v36, vcc, 0xc000, v44
	v_mov_b32_e32 v42, v1
	s_nop 0
	v_addc_co_u32_e32 v37, vcc, 0, v45, vcc
	global_store_byte v[36:37], v0, off
	v_add_co_u32_e32 v36, vcc, 0x40000, v44
	v_cvt_pk_fp8_f32 v42, v38, v39
	s_nop 0
	v_addc_co_u32_e32 v37, vcc, 0, v45, vcc
	global_store_byte v[36:37], v41, off
	v_add_co_u32_e32 v36, vcc, 0x44000, v44
	v_lshrrev_b32_e32 v0, 8, v41
	s_nop 0
	v_addc_co_u32_e32 v37, vcc, 0, v45, vcc
	global_store_byte v[36:37], v0, off
	v_add_co_u32_e32 v36, vcc, 0x48000, v44
	v_lshrrev_b32_e32 v0, 8, v42
	s_nop 0
	v_addc_co_u32_e32 v37, vcc, 0, v45, vcc
	global_store_byte v[36:37], v42, off
	v_add_co_u32_e32 v36, vcc, 0x4c000, v44
	s_nop 1
	v_addc_co_u32_e32 v37, vcc, 0, v45, vcc
	global_store_byte v[36:37], v0, off

; DI unsigned pack2(float a, float b) { f2_t v = {a, b}; return __builtin_bit_cast(unsigned, __builtin_convertvector(v, bf2_t)); }
;   DI void operator()(const f32x4 (&acc)[2][2][4][2], const pg8::Unit& u, int wr, int wc, int fr, int fq) const {
;     ...
;           const int row = u.pm * 256 + ai * 128 + wr * 64 + m * 16 + fr;
;           f32x4 x1 = acc[ai][bj][m][0], x2 = acc[ai][bj][m][1];
;           if (mode != 0) {
;             const float pos = (float)(row & (S - 1));
; #pragma unroll
;             for (int e = 0; e < 4; ++e) {
;               const float ang = __fmul_rn(pos, invv[e]);
;               float sn, cs; sincos_big(ang, sn, cs);
;               const float y1 = x1[e] * cs - x2[e] * sn, y2 = x2[e] * cs + x1[e] * sn;
;               x1[e] = y1; x2[e] = y2;
;             }
;           }
;           u16* dp = proj + (size_t)row * NPROJ;
;           *(uint2*)(dp + c1) = make_uint2(pack2(x1[0] * scale, x1[1] * scale), pack2(x1[2] * scale, x1[3] * scale));
;           *(uint2*)(dp + c2) = make_uint2(pack2(x2[0] * scale, x2[1] * scale), pack2(x2[2] * scale, x2[3] * scale));
;           if (gcol0 >= 512 && gcol0 < 768) {
;             const int hd = (gcol0 - 512) >> 6, d0 = (gcol0 & 63) + 4 * fq;
;             unsigned char* vp = vt8 + ((size_t)((row >> 14) * 4 + hd) * 64 + d0) * S + (row & (S - 1));
;             const int w1a = __builtin_amdgcn_cvt_pk_fp8_f32(x1[0], x1[1], 0, false), w1b = __builtin_amdgcn_cvt_pk_fp8_f32(x1[2], x1[3], 0, false);
;             const int w2a = __builtin_amdgcn_cvt_pk_fp8_f32(x2[0], x2[1], 0, false), w2b = __builtin_amdgcn_cvt_pk_fp8_f32(x2[2], x2[3], 0, false);
;             vp[0] = (unsigned char)(w1a & 0xff); vp[(size_t)S] = (unsigned char)((w1a >> 8) & 0xff); vp[(size_t)2 * S] = (unsigned char)(w1b & 0xff); vp[(size_t)3 * S] = (unsigned char)((w1b >> 8) & 0xff);
;             unsigned char* vq = vp + (size_t)16 * S;
;             vq[0] = (unsigned char)(w2a & 0xff); vq[(size_t)S] = (unsigned char)((w2a >> 8) & 0xff); vq[(size_t)2 * S] = (unsigned char)(w2b & 0xff); vq[(size_t)3 * S] = (unsigned char)((w2b >> 8) & 0xff);
;           }
.LBB0_195:
	v_pk_mul_f32 v[36:37], v[84:85], v[32:33]
	v_pk_mul_f32 v[38:39], v[84:85], v[34:35]
	v_cvt_pk_bf16_f32 v36, v36, v37
	v_cvt_pk_bf16_f32 v37, v38, v39
	v_lshl_add_u64 v[38:39], v[88:89], 1, v[102:103]
	v_bfe_u32 v222, v227, 4, 1
	v_mul_u32_u24_e32 v222, 0x17ff8, v222
	v_mov_b32_e32 v223, 0
	v_mov_b32_e32 v200, v36
	v_mov_b32_e32 v201, v37
	v_lshl_add_u64 v[204:205], v[38:39], 0, v[222:223]
	v_pk_mul_f32 v[36:37], v[84:85], v[10:11]
	v_pk_mul_f32 v[38:39], v[84:85], v[12:13]
	v_cvt_pk_bf16_f32 v36, v36, v37
	v_cvt_pk_bf16_f32 v37, v38, v39
	v_lshl_add_u64 v[38:39], v[86:87], 1, v[102:103]
	s_and_b64 vcc, exec, s[40:41]
	v_mov_b32_e32 v208, v36
	v_mov_b32_e32 v209, v37
	v_lshl_add_u64 v[212:213], v[38:39], 0, v[222:223]
	s_cbranch_vccnz .LBB0_197
	v_mov_b32_e32 v0, v1
	v_cvt_pk_fp8_f32 v0, v32, v33
	v_mov_b32_e32 v101, v1
	v_lshl_add_u64 v[36:37], v[52:53], 0, v[100:101]
	v_mov_b32_e32 v32, v1
	v_mov_b32_e32 v33, v1
	v_cvt_pk_fp8_f32 v32, v34, v35
	v_cvt_pk_fp8_f32 v33, v10, v11
	v_add_co_u32_e32 v10, vcc, 0x4000, v36
	global_store_byte v[36:37], v0, off
	v_lshrrev_b32_e32 v0, 8, v0
	v_addc_co_u32_e32 v11, vcc, 0, v37, vcc
	global_store_byte v[10:11], v0, off
	v_add_co_u32_e32 v10, vcc, 0x8000, v36
	v_lshrrev_b32_e32 v0, 8, v32
	s_nop 0
	v_addc_co_u32_e32 v11, vcc, 0, v37, vcc
	global_store_byte v[10:11], v32, off
	v_add_co_u32_e32 v10, vcc, 0xc000, v36
	v_mov_b32_e32 v34, v1
	s_nop 0
	v_addc_co_u32_e32 v11, vcc, 0, v37, vcc
	global_store_byte v[10:11], v0, off
	v_add_co_u32_e32 v10, vcc, 0x40000, v36
	v_cvt_pk_fp8_f32 v34, v12, v13
	s_nop 0
	v_addc_co_u32_e32 v11, vcc, 0, v37, vcc
	global_store_byte v[10:11], v33, off
	v_add_co_u32_e32 v10, vcc, 0x44000, v36
	v_lshrrev_b32_e32 v0, 8, v33
	s_nop 0
	v_addc_co_u32_e32 v11, vcc, 0, v37, vcc
	global_store_byte v[10:11], v0, off
	v_add_co_u32_e32 v10, vcc, 0x48000, v36
	v_lshrrev_b32_e32 v0, 8, v34
	s_nop 0
	v_addc_co_u32_e32 v11, vcc, 0, v37, vcc
	global_store_byte v[10:11], v34, off
	v_add_co_u32_e32 v10, vcc, 0x4c000, v36
	s_nop 1
	v_addc_co_u32_e32 v11, vcc, 0, v37, vcc
	global_store_byte v[10:11], v0, off

; DI unsigned pack2(float a, float b) { f2_t v = {a, b}; return __builtin_bit_cast(unsigned, __builtin_convertvector(v, bf2_t)); }
;   DI void operator()(const f32x4 (&acc)[2][2][4][2], const pg8::Unit& u, int wr, int wc, int fr, int fq) const {
;     ...
;           const int row = u.pm * 256 + ai * 128 + wr * 64 + m * 16 + fr;
;           f32x4 x1 = acc[ai][bj][m][0], x2 = acc[ai][bj][m][1];
;           if (mode != 0) {
;             const float pos = (float)(row & (S - 1));
; #pragma unroll
;             for (int e = 0; e < 4; ++e) {
;               const float ang = __fmul_rn(pos, invv[e]);
;               float sn, cs; sincos_big(ang, sn, cs);
;               const float y1 = x1[e] * cs - x2[e] * sn, y2 = x2[e] * cs + x1[e] * sn;
;               x1[e] = y1; x2[e] = y2;
;             }
;           }
;           u16* dp = proj + (size_t)row * NPROJ;
;           *(uint2*)(dp + c1) = make_uint2(pack2(x1[0] * scale, x1[1] * scale), pack2(x1[2] * scale, x1[3] * scale));
;           *(uint2*)(dp + c2) = make_uint2(pack2(x2[0] * scale, x2[1] * scale), pack2(x2[2] * scale, x2[3] * scale));
;           if (gcol0 >= 512 && gcol0 < 768) {
;             const int hd = (gcol0 - 512) >> 6, d0 = (gcol0 & 63) + 4 * fq;
;             unsigned char* vp = vt8 + ((size_t)((row >> 14) * 4 + hd) * 64 + d0) * S + (row & (S - 1));
;             const int w1a = __builtin_amdgcn_cvt_pk_fp8_f32(x1[0], x1[1], 0, false), w1b = __builtin_amdgcn_cvt_pk_fp8_f32(x1[2], x1[3], 0, false);
;             const int w2a = __builtin_amdgcn_cvt_pk_fp8_f32(x2[0], x2[1], 0, false), w2b = __builtin_amdgcn_cvt_pk_fp8_f32(x2[2], x2[3], 0, false);
;             vp[0] = (unsigned char)(w1a & 0xff); vp[(size_t)S] = (unsigned char)((w1a >> 8) & 0xff); vp[(size_t)2 * S] = (unsigned char)(w1b & 0xff); vp[(size_t)3 * S] = (unsigned char)((w1b >> 8) & 0xff);
;             unsigned char* vq = vp + (size_t)16 * S;
;             vq[0] = (unsigned char)(w2a & 0xff); vq[(size_t)S] = (unsigned char)((w2a >> 8) & 0xff); vq[(size_t)2 * S] = (unsigned char)(w2b & 0xff); vq[(size_t)3 * S] = (unsigned char)((w2b >> 8) & 0xff);
;           }
.LBB0_199:
	v_pk_mul_f32 v[10:11], v[84:85], v[6:7]
	v_pk_mul_f32 v[12:13], v[84:85], v[8:9]
	v_cvt_pk_bf16_f32 v10, v10, v11
	v_cvt_pk_bf16_f32 v11, v12, v13
	v_lshl_add_u64 v[12:13], v[88:89], 1, v[94:95]
	v_mov_b32_e32 v202, v10
	v_mov_b32_e32 v203, v11
	s_nop 1
	v_permlane16_swap_b32_e32 v200, v202
	v_permlane16_swap_b32_e32 v201, v203
	global_store_dwordx4 v[204:205], v[200:203], off
	v_pk_mul_f32 v[10:11], v[84:85], v[2:3]
	v_pk_mul_f32 v[12:13], v[84:85], v[4:5]
	v_cvt_pk_bf16_f32 v10, v10, v11
	v_cvt_pk_bf16_f32 v11, v12, v13
	v_lshl_add_u64 v[12:13], v[86:87], 1, v[94:95]
	s_and_b64 vcc, exec, s[40:41]
	v_mov_b32_e32 v210, v10
	v_mov_b32_e32 v211, v11
	s_nop 1
	v_permlane16_swap_b32_e32 v208, v210
	v_permlane16_swap_b32_e32 v209, v211
	global_store_dwordx4 v[212:213], v[208:211], off
	s_cbranch_vccnz .LBB0_112
	v_mov_b32_e32 v0, v1
	v_cvt_pk_fp8_f32 v0, v6, v7
	v_mov_b32_e32 v93, v1
	v_lshl_add_u64 v[10:11], v[52:53], 0, v[92:93]
	v_mov_b32_e32 v6, v1
	v_mov_b32_e32 v7, v1
	v_cvt_pk_fp8_f32 v6, v8, v9
	v_cvt_pk_fp8_f32 v7, v2, v3
	v_add_co_u32_e32 v2, vcc, 0x4000, v10
	global_store_byte v[10:11], v0, off
	v_lshrrev_b32_e32 v0, 8, v0
	v_addc_co_u32_e32 v3, vcc, 0, v11, vcc
	global_store_byte v[2:3], v0, off
	v_add_co_u32_e32 v2, vcc, 0x8000, v10
	v_lshrrev_b32_e32 v0, 8, v6
	s_nop 0
	v_addc_co_u32_e32 v3, vcc, 0, v11, vcc
	global_store_byte v[2:3], v6, off
	v_add_co_u32_e32 v2, vcc, 0xc000, v10
	v_mov_b32_e32 v8, v1
	s_nop 0
	v_addc_co_u32_e32 v3, vcc, 0, v11, vcc
	global_store_byte v[2:3], v0, off
	v_add_co_u32_e32 v2, vcc, 0x40000, v10
	v_cvt_pk_fp8_f32 v8, v4, v5
	s_nop 0
	v_addc_co_u32_e32 v3, vcc, 0, v11, vcc
	global_store_byte v[2:3], v7, off
	v_add_co_u32_e32 v2, vcc, 0x44000, v10
	v_lshrrev_b32_e32 v0, 8, v7
	s_nop 0
	v_addc_co_u32_e32 v3, vcc, 0, v11, vcc
	global_store_byte v[2:3], v0, off
	v_add_co_u32_e32 v2, vcc, 0x48000, v10
	v_lshrrev_b32_e32 v0, 8, v8
	s_nop 0
	v_addc_co_u32_e32 v3, vcc, 0, v11, vcc
	global_store_byte v[2:3], v8, off
	v_add_co_u32_e32 v2, vcc, 0x4c000, v10
	s_nop 1
	v_addc_co_u32_e32 v3, vcc, 0, v11, vcc
	global_store_byte v[2:3], v0, off
	s_branch .LBB0_112
